# KLT stored fragment-contiguous by gla_prep; scan/local phases load 1KiB-contiguous MFMA fragments instead of 32 partial lines per wave load
# speedup vs baseline: 1.0499x; 1.0316x over previous
.LBB0_202:
	s_lshr_b32 s30, s23, 6
	s_lshl_b32 s30, s30, 19
	s_bfe_u32 s31, s23, 0x20004
	s_lshl_b32 s31, s31, 22
	s_or_b32 s30, s30, s31
	s_lshr_b32 s6, s23, 4
	v_lshlrev_b32_e32 v34, 14, v200
	s_and_b32 s6, s6, 3
	v_lshl_or_b32 v34, s3, 23, v34
	s_lshl_b32 s3, s23, 5
	s_lshl_b32 s66, s6, 9
	s_and_b32 s24, s3, 0x1e0
	s_or_b32 s3, s24, s66
	s_lshl_b32 s18, s2, 4
	s_lshl_b32 s2, s2, 10
	v_or_b32_e32 v42, s3, v200
	s_ashr_i32 s19, s18, 31
	s_ashr_i32 s3, s2, 31
	s_lshl_b32 s25, s6, 10
	s_lshl_b32 s28, s5, 6
	v_add_u32_e32 v32, s4, v201
	s_lshl_b32 s4, s6, 13
	v_lshl_or_b32 v34, s5, 19, v34
	v_lshl_add_u32 v36, s6, 8, v201
	s_mov_b32 s5, s67
	s_lshl_b64 s[16:17], s[18:19], 17
	s_lshl_b64 s[6:7], s[18:19], 15
	s_lshl_b64 s[8:9], s[2:3], 1
	s_lshl_b64 s[2:3], s[18:19], 18
	s_lshl_b64 s[18:19], s[18:19], 12
	v_lshl_add_u64 v[40:41], v[158:159], 0, s[4:5]
	s_add_u32 s5, s20, s18
	v_lshl_add_u64 v[38:39], v[156:157], 0, s[66:67]
	s_addc_u32 s27, s21, s19
	v_lshl_add_u64 v[38:39], v[38:39], 0, s[16:17]
	s_add_u32 s26, s5, s25
	s_mov_b32 s5, 0x10000
	v_ashrrev_i32_e32 v37, 31, v36
	v_lshl_add_u64 v[40:41], v[40:41], 0, s[6:7]
	global_load_dwordx4 v[96:99], v[38:39], off
	global_load_dwordx4 v[88:91], v[38:39], off offset:32
	global_load_dwordx4 v[80:83], v[38:39], off offset:64
	global_load_dwordx4 v[72:75], v[38:39], off offset:96
	global_load_dwordx4 v[64:67], v[40:41], off
	v_add_co_u32_e32 v38, vcc, s5, v38
	v_lshlrev_b64 v[36:37], 14, v[36:37]
	s_nop 0
	v_addc_co_u32_e32 v39, vcc, 0, v39, vcc
	v_lshlrev_b32_e32 v42, 14, v42
	v_mov_b32_e32 v43, v187
	v_lshl_add_u64 v[36:37], v[162:163], 0, v[36:37]
	global_load_dwordx4 v[100:103], v[38:39], off
	global_load_dwordx4 v[92:95], v[38:39], off offset:32
	global_load_dwordx4 v[84:87], v[38:39], off offset:64
	global_load_dwordx4 v[76:79], v[38:39], off offset:96
	v_add_co_u32_e32 v38, vcc, s29, v40
	v_lshl_add_u64 v[42:43], v[160:161], 0, v[42:43]
	s_nop 0
	v_addc_co_u32_e32 v39, vcc, 0, v41, vcc
	v_lshl_add_u64 v[36:37], v[36:37], 0, s[8:9]
	v_lshl_add_u64 v[42:43], v[42:43], 0, s[8:9]
	global_load_dwordx4 v[68:71], v[38:39], off
	global_load_dwordx4 v[108:111], v[42:43], off
	global_load_dwordx4 v[104:107], v[42:43], off offset:32
	global_load_dwordx4 v[112:115], v[42:43], off offset:64
	global_load_dwordx4 v[116:119], v[42:43], off offset:96
	v_lshrrev_b32_e32 v214, 6, v152
	v_and_b32_e32 v215, 63, v152
	v_lshlrev_b32_e32 v214, 13, v214
	v_lshl_or_b32 v214, v215, 4, v214
	v_add_u32_e32 v194, s30, v214
	v_mov_b32_e32 v195, 0
	v_lshl_add_u64 v[36:37], s[0:1], 0, v[194:195]
	v_add_co_u32_e32 v36, vcc, 0xd001000, v36
	s_nop 1
	v_addc_co_u32_e32 v37, vcc, 0, v37, vcc
	global_load_dwordx4 v[148:151], v[36:37], off offset:-4096
	global_load_dwordx4 v[144:147], v[36:37], off offset:-3072
	global_load_dwordx4 v[140:143], v[36:37], off offset:-2048
	global_load_dwordx4 v[136:139], v[36:37], off offset:-1024
	s_addc_u32 s27, s27, 0
	s_nop 0
	global_load_dwordx4 v[132:135], v[36:37], off
	global_load_dwordx4 v[128:131], v[36:37], off offset:1024
	global_load_dwordx4 v[124:127], v[36:37], off offset:2048
	global_load_dwordx4 v[120:123], v[36:37], off offset:3072
	v_lshl_add_u64 v[36:37], v[152:153], 2, s[26:27]
	s_barrier
	global_load_dword v36, v[36:37], off
	v_ashrrev_i32_e32 v33, 31, v32
	v_lshlrev_b64 v[32:33], 14, v[32:33]
	s_or_b32 s18, s18, s25
	v_mov_b32_e32 v35, v187
	v_lshl_add_u64 v[180:181], s[18:19], 0, v[170:171]
	s_or_b32 s18, s28, s25
	v_or_b32_e32 v32, v154, v32
	s_or_b32 s18, s2, s18
	s_mov_b32 s19, s3
	s_or_b32 s16, s16, s66
	s_or_b32 s6, s6, s4
	v_lshl_add_u64 v[32:33], v[178:179], 0, v[34:35]
	s_mov_b32 s5, 0
	v_lshl_add_u64 v[182:183], s[18:19], 0, v[172:173]
	v_lshl_add_u64 v[192:193], s[16:17], 0, v[174:175]
	v_lshl_add_u64 v[196:197], s[6:7], 0, v[176:177]
	v_lshl_add_u64 v[198:199], v[32:33], 0, s[8:9]
	s_waitcnt vmcnt(0)
	ds_write_b32 v155, v36 offset:32768
	s_waitcnt lgkmcnt(0)
	s_barrier
.LBB0_203:
	v_lshl_add_u64 v[32:33], s[0:1], 0, v[180:181]
	global_load_dword v205, v[32:33], off
	v_cvt_pk_bf16_f32 v32, v16, v17
	v_cvt_pk_bf16_f32 v33, v18, v19
	v_cvt_pk_bf16_f32 v34, v20, v21
	v_cvt_pk_bf16_f32 v35, v22, v23
	s_mov_b32 s4, 0xc020000
	s_waitcnt vmcnt(10)
	v_cndmask_b32_e64 v206, v119, v115, s[14:15]
	v_mfma_f32_32x32x16_bf16 v[48:63], v[96:99], v[32:35], 0
	v_cvt_pk_bf16_f32 v96, v24, v25
	v_cvt_pk_bf16_f32 v97, v26, v27
	v_cvt_pk_bf16_f32 v98, v28, v29
	v_cvt_pk_bf16_f32 v99, v30, v31
	v_cndmask_b32_e64 v207, v118, v114, s[14:15]
	v_cndmask_b32_e64 v208, v117, v113, s[14:15]
	v_cndmask_b32_e64 v209, v116, v112, s[14:15]
	v_mfma_f32_32x32x16_bf16 v[48:63], v[88:91], v[96:99], v[48:63]
	v_cvt_pk_bf16_f32 v88, v0, v1
	v_cvt_pk_bf16_f32 v89, v2, v3
	v_cvt_pk_bf16_f32 v90, v4, v5
	v_cvt_pk_bf16_f32 v91, v6, v7
	v_cndmask_b32_e64 v210, v209, v104, s[12:13]
	v_cndmask_b32_e64 v211, v208, v105, s[12:13]
	v_cndmask_b32_e64 v207, v207, v106, s[12:13]
	v_mfma_f32_32x32x16_bf16 v[32:47], v[100:103], v[32:35], 0
	v_cndmask_b32_e64 v206, v206, v107, s[12:13]
	v_cndmask_b32_e64 v209, v206, v111, s[10:11]
	v_cndmask_b32_e64 v208, v207, v110, s[10:11]
	v_cndmask_b32_e64 v207, v211, v109, s[10:11]
	v_cndmask_b32_e64 v206, v210, v108, s[10:11]
	v_add_u32_e32 v210, 0x1800, v204
	v_add_u32_e32 v211, 0x1c00, v204
	v_mfma_f32_32x32x16_bf16 v[48:63], v[80:83], v[88:91], v[48:63]
	v_cvt_pk_bf16_f32 v80, v8, v9
	v_cvt_pk_bf16_f32 v81, v10, v11
	v_cvt_pk_bf16_f32 v82, v12, v13
	v_cvt_pk_bf16_f32 v83, v14, v15
	s_mov_b64 s[6:7], 0x8000
	v_lshl_add_u64 v[180:181], v[180:181], 0, s[86:87]
	s_waitcnt vmcnt(2)
	v_mfma_f32_32x32x16_bf16 v[16:31], v[148:151], v[108:111], v[16:31]
	v_mfma_f32_32x32x16_bf16 v[0:15], v[132:135], v[108:111], v[0:15]
	v_mfma_f32_32x32x16_bf16 v[32:47], v[92:95], v[96:99], v[32:47]
	v_mfma_f32_32x32x16_bf16 v[16:31], v[144:147], v[104:107], v[16:31]
	v_mfma_f32_32x32x16_bf16 v[0:15], v[128:131], v[104:107], v[0:15]
	v_mfma_f32_32x32x16_bf16 v[32:47], v[84:87], v[88:91], v[32:47]
	v_mfma_f32_32x32x16_bf16 v[48:63], v[72:75], v[80:83], v[48:63]
	v_mfma_f32_32x32x16_bf16 v[16:31], v[140:143], v[112:115], v[16:31]
	v_mfma_f32_32x32x16_bf16 v[0:15], v[124:127], v[112:115], v[0:15]
	v_mfma_f32_32x32x16_bf16 v[32:47], v[76:79], v[80:83], v[32:47]
	v_lshl_add_u64 v[76:77], s[0:1], 0, v[192:193]
	v_add_co_u32_e32 v72, vcc, s4, v76
	s_mov_b32 s4, 0xc030000
	s_nop 0
	v_addc_co_u32_e32 v73, vcc, 0, v77, vcc
	v_add_co_u32_e32 v76, vcc, s4, v76
	v_mfma_f32_32x32x16_bf16 v[48:63], v[64:67], v[206:209], v[48:63]
	s_nop 0
	v_addc_co_u32_e32 v77, vcc, 0, v77, vcc
	v_lshl_add_u64 v[64:65], s[0:1], 0, v[196:197]
	s_mov_b32 s4, 0xe009000
	global_load_dwordx4 v[96:99], v[72:73], off
	global_load_dwordx4 v[88:91], v[72:73], off offset:32
	global_load_dwordx4 v[80:83], v[72:73], off offset:64
	s_nop 0
	global_load_dwordx4 v[72:75], v[72:73], off offset:96
	s_nop 0
	global_load_dwordx4 v[100:103], v[76:77], off
	global_load_dwordx4 v[92:95], v[76:77], off offset:32
	global_load_dwordx4 v[84:87], v[76:77], off offset:64
	s_nop 0
	global_load_dwordx4 v[76:79], v[76:77], off offset:96
	v_lshl_add_u64 v[192:193], v[192:193], 0, s[58:59]
	v_mfma_f32_32x32x16_bf16 v[16:31], v[136:139], v[116:119], v[16:31]
	v_lshl_add_u64 v[196:197], v[196:197], 0, s[6:7]
	v_mfma_f32_32x32x16_bf16 v[0:15], v[120:123], v[116:119], v[0:15]
	v_lshl_add_u64 v[116:117], s[0:1], 0, v[198:199]
	v_lshl_add_u64 v[198:199], v[198:199], 0, s[94:95]
	v_mfma_f32_32x32x16_bf16 v[32:47], v[68:71], v[206:209], v[32:47]
	v_add_co_u32_e32 v68, vcc, s4, v64
	s_and_b32 s4, s5, 0x100
	s_nop 0
	v_addc_co_u32_e32 v69, vcc, 0, v65, vcc
	v_lshl_add_u32 v206, s4, 2, v202
	global_load_dwordx4 v[64:67], v[68:69], off offset:-4096
	s_nop 0
	global_load_dwordx4 v[68:71], v[68:69], off
	ds_read_b128 v[136:139], v206 offset:32768
	ds_read_b128 v[140:143], v206 offset:32800
	ds_read_b128 v[104:107], v206 offset:32896
	s_mov_b32 s4, 0xd080000
	s_addk_i32 s5, 0x100
	s_waitcnt lgkmcnt(2)
	v_pk_mul_f32 v[16:17], v[16:17], v[136:137]
	v_pk_mul_f32 v[18:19], v[18:19], v[138:139]
	ds_read_b128 v[136:139], v206 offset:32832
	s_waitcnt lgkmcnt(1)
	v_pk_mul_f32 v[0:1], v[0:1], v[104:105]
	v_pk_mul_f32 v[2:3], v[2:3], v[106:107]
	ds_read_b128 v[104:107], v206 offset:32928
	v_pk_mul_f32 v[20:21], v[20:21], v[140:141]
	s_waitcnt lgkmcnt(1)
	v_pk_mul_f32 v[24:25], v[24:25], v[136:137]
	v_pk_mul_f32 v[26:27], v[26:27], v[138:139]
	ds_read_b128 v[136:139], v206 offset:32864
	s_waitcnt lgkmcnt(1)
	v_pk_mul_f32 v[4:5], v[4:5], v[104:105]
	v_pk_mul_f32 v[6:7], v[6:7], v[106:107]
	ds_read_b128 v[104:107], v206 offset:32960
	v_pk_mul_f32 v[22:23], v[22:23], v[142:143]
	s_waitcnt lgkmcnt(1)
	v_pk_mul_f32 v[28:29], v[28:29], v[136:137]
	v_lshl_add_u64 v[136:137], s[0:1], 0, v[194:195]
	v_add_co_u32_e32 v212, vcc, 0xd009000, v136
	s_waitcnt lgkmcnt(0)
	v_pk_mul_f32 v[8:9], v[8:9], v[104:105]
	v_pk_mul_f32 v[10:11], v[10:11], v[106:107]
	ds_read_b128 v[104:107], v206 offset:32992
	v_addc_co_u32_e32 v213, vcc, 0, v137, vcc
	v_pk_mul_f32 v[30:31], v[30:31], v[138:139]
	s_nop 0
	s_waitcnt lgkmcnt(0)
	v_pk_mul_f32 v[12:13], v[12:13], v[104:105]
	v_pk_mul_f32 v[14:15], v[14:15], v[106:107]
	global_load_dwordx4 v[108:111], v[116:117], off offset:-64
	global_load_dwordx4 v[104:107], v[116:117], off offset:-32
	global_load_dwordx4 v[112:115], v[116:117], off
	s_nop 0
	global_load_dwordx4 v[116:119], v[116:117], off offset:32
	s_nop 0
	global_load_dwordx4 v[120:123], v[212:213], off offset:3072
	global_load_dwordx4 v[124:127], v[212:213], off offset:2048
	global_load_dwordx4 v[128:131], v[212:213], off offset:1024
	global_load_dwordx4 v[132:135], v[212:213], off
	global_load_dwordx4 v[136:139], v[212:213], off offset:-1024
	global_load_dwordx4 v[140:143], v[212:213], off offset:-2048
	global_load_dwordx4 v[144:147], v[212:213], off offset:-3072
	global_load_dwordx4 v[148:151], v[212:213], off offset:-4096
	s_and_b32 s4, s5, 0x100
	v_lshl_add_u32 v206, s4, 2, v155
	s_waitcnt vmcnt(22)
	ds_write_b32 v206, v205 offset:32768
	ds_write2_b32 v204, v48, v49 offset1:32
	ds_write2_b32 v204, v50, v51 offset0:64 offset1:96
	v_add_u32_e32 v205, 0x400, v204
	v_add_u32_e32 v206, 0x800, v204
	v_add_u32_e32 v207, 0xc00, v204
	v_add_u32_e32 v208, 0x1000, v204
	v_add_u32_e32 v209, 0x1400, v204
	ds_write2_b32 v205, v52, v53 offset1:32
	ds_write2_b32 v205, v54, v55 offset0:64 offset1:96
	ds_write2_b32 v206, v56, v57 offset1:32
	ds_write2_b32 v206, v58, v59 offset0:64 offset1:96
	ds_write2_b32 v207, v60, v61 offset1:32
	ds_write2_b32 v207, v62, v63 offset0:64 offset1:96
	ds_write2_b32 v208, v32, v33 offset1:32
	ds_write2_b32 v208, v34, v35 offset0:64 offset1:96
	ds_write2_b32 v209, v36, v37 offset1:32
	ds_write2_b32 v209, v38, v39 offset0:64 offset1:96
	ds_write2_b32 v210, v40, v41 offset1:32
	ds_write2_b32 v210, v42, v43 offset0:64 offset1:96
	ds_write2_b32 v211, v44, v45 offset1:32
	ds_write2_b32 v211, v46, v47 offset0:64 offset1:96
	s_waitcnt lgkmcnt(0)
	s_barrier
	ds_read_b128 v[32:35], v203
	ds_read_b128 v[36:39], v203 offset:16
	ds_read_b128 v[40:43], v203 offset:8192
	ds_read_b128 v[44:47], v203 offset:16384
	ds_read_b128 v[48:51], v203 offset:24576
	v_lshl_add_u64 v[194:195], v[194:195], 0, s[6:7]
	s_cmpk_eq_i32 s5, 0xf00
	s_waitcnt lgkmcnt(2)
	v_pk_add_f32 v[32:33], v[32:33], v[40:41]
	s_waitcnt lgkmcnt(1)
	v_pk_add_f32 v[32:33], v[32:33], v[44:45]
	s_waitcnt lgkmcnt(0)
	v_pk_add_f32 v[48:49], v[32:33], v[48:49]
	v_pk_add_f32 v[32:33], v[34:35], v[42:43]
	ds_read_b128 v[40:43], v203 offset:16400
	v_pk_add_f32 v[32:33], v[32:33], v[46:47]
	ds_read_b128 v[44:47], v203 offset:24592
	v_pk_add_f32 v[50:51], v[32:33], v[50:51]
	ds_read_b128 v[32:35], v203 offset:8208
	s_waitcnt lgkmcnt(0)
	v_pk_add_f32 v[32:33], v[36:37], v[32:33]
	s_nop 0
	v_pk_add_f32 v[32:33], v[32:33], v[40:41]
	s_nop 0
	v_pk_add_f32 v[36:37], v[32:33], v[44:45]
	v_pk_add_f32 v[32:33], v[38:39], v[34:35]
	v_cvt_pk_bf16_f32 v34, v36, v37
	v_pk_add_f32 v[32:33], v[32:33], v[42:43]
	v_lshl_add_u64 v[36:37], s[0:1], 0, v[182:183]
	v_pk_add_f32 v[38:39], v[32:33], v[46:47]
	v_cvt_pk_bf16_f32 v32, v48, v49
	v_cvt_pk_bf16_f32 v33, v50, v51
	v_cvt_pk_bf16_f32 v35, v38, v39
	v_lshl_add_u64 v[182:183], v[182:183], 0, s[90:91]
	global_store_dwordx4 v[36:37], v[32:35], off offset:-8
	s_barrier
	s_cbranch_scc0 .LBB0_203
	v_cvt_pk_bf16_f32 v16, v16, v17
	v_cvt_pk_bf16_f32 v17, v18, v19
	v_cvt_pk_bf16_f32 v18, v20, v21
	v_cvt_pk_bf16_f32 v19, v22, v23
	v_cvt_pk_bf16_f32 v0, v0, v1
	v_cvt_pk_bf16_f32 v1, v2, v3
	s_waitcnt vmcnt(22)
	v_mfma_f32_32x32x16_bf16 v[48:63], v[96:99], v[16:19], 0
	v_cvt_pk_bf16_f32 v2, v4, v5
	v_cvt_pk_bf16_f32 v3, v6, v7
	v_cvt_pk_bf16_f32 v4, v8, v9
	v_cvt_pk_bf16_f32 v5, v10, v11
	v_cvt_pk_bf16_f32 v6, v12, v13
	v_cvt_pk_bf16_f32 v7, v14, v15
	s_lshl_b32 s66, s66, 1
	s_waitcnt vmcnt(18)
	v_mfma_f32_32x32x16_bf16 v[32:47], v[100:103], v[16:19], 0
	v_cvt_pk_bf16_f32 v16, v24, v25
	v_cvt_pk_bf16_f32 v17, v26, v27
	v_cvt_pk_bf16_f32 v18, v28, v29
	v_cvt_pk_bf16_f32 v19, v30, v31
	s_add_i32 s23, s23, s64
	s_add_i32 s22, s22, s64
	v_mfma_f32_32x32x16_bf16 v[48:63], v[88:91], v[16:19], v[48:63]
	s_waitcnt vmcnt(17)
	v_mfma_f32_32x32x16_bf16 v[32:47], v[92:95], v[16:19], v[32:47]
	v_mfma_f32_32x32x16_bf16 v[48:63], v[80:83], v[0:3], v[48:63]
	s_waitcnt vmcnt(16)
	v_mfma_f32_32x32x16_bf16 v[32:47], v[84:87], v[0:3], v[32:47]
	s_waitcnt vmcnt(9)
	v_cndmask_b32_e64 v0, v119, v115, s[14:15]
	v_cndmask_b32_e64 v1, v118, v114, s[14:15]
	v_cndmask_b32_e64 v2, v117, v113, s[14:15]
	v_cndmask_b32_e64 v3, v116, v112, s[14:15]
	v_cndmask_b32_e64 v8, v3, v104, s[12:13]
	v_cndmask_b32_e64 v9, v2, v105, s[12:13]
	v_cndmask_b32_e64 v1, v1, v106, s[12:13]
	v_mfma_f32_32x32x16_bf16 v[48:63], v[72:75], v[4:7], v[48:63]
	v_cndmask_b32_e64 v0, v0, v107, s[12:13]
	v_cndmask_b32_e64 v3, v0, v111, s[10:11]
	v_cndmask_b32_e64 v2, v1, v110, s[10:11]
	v_cndmask_b32_e64 v1, v9, v109, s[10:11]
	v_cndmask_b32_e64 v0, v8, v108, s[10:11]
	v_lshl_add_u64 v[8:9], v[164:165], 0, s[66:67]
	s_lshl_b32 s66, s24, 1
	v_mfma_f32_32x32x16_bf16 v[32:47], v[76:79], v[4:7], v[32:47]
	v_lshl_add_u64 v[8:9], v[8:9], 0, s[66:67]
	v_lshl_add_u64 v[8:9], v[8:9], 0, v[186:187]
	s_cmpk_gt_i32 s23, 0x1ff
	v_mfma_f32_32x32x16_bf16 v[48:63], v[64:67], v[0:3], v[48:63]
	v_lshl_add_u64 v[64:65], v[8:9], 0, s[2:3]
	ds_write_b32 v155, v187 offset:32768
	s_nop 9
	ds_write2_b32 v204, v48, v49 offset1:32
	v_mfma_f32_32x32x16_bf16 v[32:47], v[68:71], v[0:3], v[32:47]
	ds_write2_b32 v204, v50, v51 offset0:64 offset1:96
	ds_write2_b32 v205, v52, v53 offset1:32
	ds_write2_b32 v205, v54, v55 offset0:64 offset1:96
	ds_write2_b32 v206, v56, v57 offset1:32
	ds_write2_b32 v206, v58, v59 offset0:64 offset1:96
	ds_write2_b32 v207, v60, v61 offset1:32
	ds_write2_b32 v207, v62, v63 offset0:64 offset1:96
	s_nop 4
	ds_write2_b32 v208, v32, v33 offset1:32
	ds_write2_b32 v208, v34, v35 offset0:64 offset1:96
	ds_write2_b32 v209, v36, v37 offset1:32
	ds_write2_b32 v209, v38, v39 offset0:64 offset1:96
	ds_write2_b32 v210, v40, v41 offset1:32
	ds_write2_b32 v210, v42, v43 offset0:64 offset1:96
	ds_write2_b32 v211, v44, v45 offset1:32
	ds_write2_b32 v211, v46, v47 offset0:64 offset1:96
	s_waitcnt lgkmcnt(0)
	s_barrier
	ds_read_b128 v[0:3], v203 offset:8192
	ds_read_b128 v[4:7], v203
	ds_read_b128 v[8:11], v203 offset:16
	ds_read_b128 v[12:15], v203 offset:16384
	ds_read_b128 v[16:19], v203 offset:24576
	ds_read_b128 v[20:23], v203 offset:8208
	ds_read_b128 v[24:27], v203 offset:16400
	ds_read_b128 v[28:31], v203 offset:24592
	s_waitcnt lgkmcnt(6)
	v_pk_add_f32 v[0:1], v[4:5], v[0:1]
	v_pk_add_f32 v[2:3], v[6:7], v[2:3]
	s_waitcnt lgkmcnt(2)
	v_pk_add_f32 v[4:5], v[8:9], v[20:21]
	v_pk_add_f32 v[0:1], v[0:1], v[12:13]
	v_pk_add_f32 v[2:3], v[2:3], v[14:15]
	s_waitcnt lgkmcnt(1)
	v_pk_add_f32 v[4:5], v[4:5], v[24:25]
	v_pk_add_f32 v[6:7], v[10:11], v[22:23]
	v_pk_add_f32 v[0:1], v[0:1], v[16:17]
	v_pk_add_f32 v[2:3], v[2:3], v[18:19]
	s_waitcnt lgkmcnt(0)
	v_pk_add_f32 v[4:5], v[4:5], v[28:29]
	v_pk_add_f32 v[6:7], v[6:7], v[26:27]
	v_cvt_pk_bf16_f32 v0, v0, v1
	v_pk_add_f32 v[6:7], v[6:7], v[30:31]
	v_cvt_pk_bf16_f32 v1, v2, v3
	v_cvt_pk_bf16_f32 v2, v4, v5
	v_add_co_u32_e32 v4, vcc, 0x3c0000, v64
	v_cvt_pk_bf16_f32 v3, v6, v7
	s_nop 0
	v_addc_co_u32_e32 v5, vcc, 0, v65, vcc
	global_store_dwordx4 v[4:5], v[0:3], off
	s_barrier
	s_cbranch_scc0 .LBB0_198

.LBB0_210:
	s_bfe_u32 s7, s6, 0x20004
	s_and_b32 s0, s6, 15
	s_lshl_b32 s8, s0, 5
	s_lshl_b32 s9, s7, 9
	s_or_b32 s8, s9, s8
	v_or_b32_e32 v0, s8, v178
	s_ashr_i32 s1, s6, 6
	s_lshl_b32 s17, s7, 22
	s_lshl_b32 s18, s1, 19
	s_or_b32 s17, s17, s18
	s_addk_i32 s17, 0x1000
	v_lshlrev_b32_e32 v186, 14, v0
	v_lshl_add_u32 v0, s7, 8, v179
	s_lshl_b32 s8, s1, 10
	v_ashrrev_i32_e32 v1, 31, v0
	s_ashr_i32 s9, s8, 31
	v_lshlrev_b64 v[0:1], 14, v[0:1]
	s_lshl_b64 s[8:9], s[8:9], 1
	v_lshl_add_u64 v[0:1], s[10:11], 0, v[0:1]
	v_lshl_add_u64 v[0:1], v[0:1], 0, s[8:9]
	v_mov_b32_e32 v161, v187
	v_lshl_add_u64 v[166:167], v[0:1], 0, v[160:161]
	v_lshrrev_b32_e32 v188, 6, v152
	v_and_b32_e32 v190, 63, v152
	v_lshlrev_b32_e32 v188, 13, v188
	v_lshl_or_b32 v188, v190, 4, v188
	v_add_u32_e32 v220, s17, v188
	v_mov_b32_e32 v221, 0
	v_lshl_add_u64 v[220:221], s[10:11], 0, v[220:221]
	v_add_co_u32_e32 v222, vcc, 0x8000, v220
	s_nop 1
	v_addc_co_u32_e32 v223, vcc, 0, v221, vcc
	v_add_co_u32_e32 v224, vcc, 0x8000, v222
	s_nop 1
	v_addc_co_u32_e32 v225, vcc, 0, v223, vcc
	v_add_co_u32_e32 v226, vcc, 0x8000, v224
	s_nop 1
	v_addc_co_u32_e32 v227, vcc, 0, v225, vcc
	v_add_co_u32_e32 v228, vcc, 0x8000, v226
	s_nop 1
	v_addc_co_u32_e32 v229, vcc, 0, v227, vcc
	v_add_co_u32_e32 v230, vcc, 0x8000, v228
	s_nop 1
	v_addc_co_u32_e32 v231, vcc, 0, v229, vcc
	v_add_co_u32_e32 v232, vcc, 0x8000, v230
	s_nop 1
	v_addc_co_u32_e32 v233, vcc, 0, v231, vcc
	v_add_co_u32_e32 v234, vcc, 0x8000, v232
	s_nop 1
	v_addc_co_u32_e32 v235, vcc, 0, v233, vcc
	v_add_co_u32_e32 v236, vcc, 0x8000, v234
	s_nop 1
	v_addc_co_u32_e32 v237, vcc, 0, v235, vcc
	v_add_co_u32_e32 v238, vcc, 0x8000, v236
	s_nop 1
	v_addc_co_u32_e32 v239, vcc, 0, v237, vcc
	v_add_co_u32_e32 v240, vcc, 0x8000, v238
	s_nop 1
	v_addc_co_u32_e32 v241, vcc, 0, v239, vcc
	v_add_co_u32_e32 v244, vcc, 0x8000, v240
	s_nop 1
	v_addc_co_u32_e32 v245, vcc, 0, v241, vcc
	v_add_co_u32_e32 v246, vcc, 0x8000, v244
	s_nop 1
	v_addc_co_u32_e32 v247, vcc, 0, v245, vcc
	v_add_co_u32_e32 v248, vcc, 0x8000, v246
	s_nop 1
	v_addc_co_u32_e32 v249, vcc, 0, v247, vcc
	v_add_co_u32_e32 v250, vcc, 0x8000, v248
	s_nop 1
	v_addc_co_u32_e32 v251, vcc, 0, v249, vcc
	v_add_co_u32_e32 v252, vcc, 0x8000, v250
	s_nop 1
	v_addc_co_u32_e32 v253, vcc, 0, v251, vcc
	global_load_dwordx4 v[0:3], v[220:221], off offset:-4096
	v_lshl_add_u64 v[4:5], s[2:3], 0, v[186:187]
	v_lshl_add_u64 v[4:5], v[4:5], 0, s[8:9]
	v_lshl_add_u64 v[168:169], v[4:5], 0, v[160:161]
	global_load_dwordx4 v[4:7], v[168:169], off
	v_add_co_u32_e32 v164, vcc, s79, v166
	s_lshl_b32 s8, s1, 4
	s_nop 0
	v_addc_co_u32_e32 v165, vcc, 0, v167, vcc
	global_load_dwordx4 v[8:11], v[220:221], off
	global_load_dwordx4 v[32:35], v[220:221], off offset:-3072
	global_load_dwordx4 v[36:39], v[168:169], off offset:32
	global_load_dwordx4 v[40:43], v[220:221], off offset:1024
	global_load_dwordx4 v[44:47], v[220:221], off offset:-2048
	global_load_dwordx4 v[52:55], v[168:169], off offset:64
	global_load_dwordx4 v[56:59], v[220:221], off offset:2048
	global_load_dwordx4 v[60:63], v[220:221], off offset:-1024
	global_load_dwordx4 v[64:67], v[168:169], off offset:96
	s_ashr_i32 s9, s8, 31
	s_lshl_b64 s[8:9], s[8:9], 12
	s_add_u32 s14, s4, s8
	s_addc_u32 s15, s5, s9
	s_lshl_b32 s16, s7, 10
	global_load_dwordx4 v[68:71], v[220:221], off offset:3072
	s_add_u32 s14, s14, s16
	s_addc_u32 s15, s15, 0
	v_mov_b32_e32 v163, v187
	v_lshl_add_u64 v[12:13], v[154:155], 2, s[14:15]
	v_lshl_add_u64 v[170:171], v[12:13], 0, v[162:163]
	global_load_dwordx4 v[72:75], v[170:171], off offset:96
	global_load_dwordx4 v[76:79], v[170:171], off offset:64
	global_load_dwordx4 v[80:83], v[222:223], off offset:-4096
	global_load_dwordx4 v[84:87], v[170:171], off offset:32
	global_load_dwordx4 v[88:91], v[170:171], off
	global_load_dwordx4 v[92:95], v[168:169], off offset:128
	global_load_dwordx4 v[96:99], v[170:171], off offset:224
	global_load_dwordx4 v[180:183], v[170:171], off offset:192
	global_load_dwordx4 v[192:195], v[222:223], off
	global_load_dwordx4 v[196:199], v[170:171], off offset:160
	global_load_dwordx4 v[200:203], v[170:171], off offset:128
	global_load_dwordx4 v[204:207], v[222:223], off offset:-3072
	global_load_dwordx4 v[208:211], v[168:169], off offset:160
	s_movk_i32 s14, 0x3000
	s_lshl_b32 s1, s1, 2
	s_or_b32 s7, s1, s7
	s_lshl_b32 s1, s7, 4
	s_waitcnt vmcnt(23) lgkmcnt(0)
	v_mfma_f32_32x32x16_bf16 v[16:31], v[0:3], v[4:7], 0
	s_waitcnt vmcnt(22)
	v_mfma_f32_32x32x16_bf16 v[0:15], v[8:11], v[4:7], 0
	s_waitcnt vmcnt(20)
	v_mfma_f32_32x32x16_bf16 v[16:31], v[32:35], v[36:39], v[16:31]
	global_load_dwordx4 v[32:35], v[222:223], off offset:1024
	s_waitcnt vmcnt(20)
	v_mfma_f32_32x32x16_bf16 v[0:15], v[40:43], v[36:39], v[0:15]
	global_load_dwordx4 v[40:43], v[222:223], off offset:-2048
	global_load_dwordx4 v[212:215], v[168:169], off offset:192
	global_load_dwordx4 v[216:219], v[222:223], off offset:2048
	global_load_dwordx4 v[48:51], v[222:223], off offset:-1024
	global_load_dwordx4 v[108:111], v[224:225], off offset:-4096
	global_load_dwordx4 v[116:119], v[168:169], off offset:224
	global_load_dwordx4 v[124:127], v[222:223], off offset:3072
	global_load_dwordx4 v[100:103], v[224:225], off
	global_load_dwordx4 v[104:107], v[168:169], off offset:256
	v_add_co_u32_e32 v36, vcc, s29, v170
	s_nop 1
	v_addc_co_u32_e32 v37, vcc, 0, v171, vcc
	s_waitcnt vmcnt(27)
	v_mfma_f32_32x32x16_bf16 v[16:31], v[44:47], v[52:55], v[16:31]
	v_add_co_u32_e32 v174, vcc, s76, v170
	s_nop 1
	v_addc_co_u32_e32 v175, vcc, 0, v171, vcc
	global_load_dwordx4 v[128:131], v[174:175], off offset:-4096
	global_load_dwordx4 v[136:139], v[36:37], off offset:32
	global_load_dwordx4 v[144:147], v[36:37], off offset:64
	global_load_dwordx4 v[148:151], v[36:37], off offset:96
	global_load_dwordx4 v[112:115], v[36:37], off offset:128
	global_load_dwordx4 v[120:123], v[36:37], off offset:160
	global_load_dwordx4 v[132:135], v[36:37], off offset:192
	global_load_dwordx4 v[140:143], v[36:37], off offset:224
	s_waitcnt vmcnt(32)
	v_mfma_f32_32x32x16_bf16 v[16:31], v[60:63], v[64:67], v[16:31]
	v_add_co_u32_e32 v176, vcc, s14, v170
	s_mov_b32 s14, 0xf000
	s_nop 0
	v_addc_co_u32_e32 v177, vcc, 0, v171, vcc
	v_add_co_u32_e32 v172, vcc, s14, v170
	v_mfma_f32_32x32x16_bf16 v[0:15], v[56:59], v[52:55], v[0:15]
	s_waitcnt vmcnt(30)
	s_nop 4
	v_mul_f32_e64 v30, v74, v30
	v_mul_f32_e64 v31, v75, v31
	v_mul_f32_e64 v28, v72, v28
	v_mul_f32_e64 v29, v73, v29
	global_load_dwordx4 v[36:39], v[224:225], off offset:-3072
	global_load_dwordx4 v[72:75], v[168:169], off offset:288
	s_waitcnt vmcnt(31)
	v_pk_mul_f32 v[26:27], v[78:79], v[26:27]
	v_pk_mul_f32 v[24:25], v[76:77], v[24:25]
	global_load_dwordx4 v[76:79], v[224:225], off offset:1024
	s_waitcnt vmcnt(30)
	v_pk_mul_f32 v[22:23], v[86:87], v[22:23]
	v_mfma_f32_32x32x16_bf16 v[0:15], v[68:71], v[64:67], v[0:15]
	global_load_dwordx4 v[68:71], v[224:225], off offset:-2048
	global_load_dwordx4 v[52:55], v[168:169], off offset:320
	global_load_dwordx4 v[64:67], v[224:225], off offset:-1024
	global_load_dwordx4 v[44:47], v[168:169], off offset:352
	global_load_dwordx4 v[60:63], v[224:225], off offset:2048
	v_pk_mul_f32 v[20:21], v[84:85], v[20:21]
	s_waitcnt vmcnt(34)
	v_pk_mul_f32 v[18:19], v[90:91], v[18:19]
	v_pk_mul_f32 v[16:17], v[88:89], v[16:17]
	v_addc_co_u32_e32 v173, vcc, 0, v171, vcc
	s_waitcnt vmcnt(33)
	v_mfma_f32_32x32x16_bf16 v[16:31], v[80:83], v[92:95], v[16:31]
	s_waitcnt vmcnt(32)
	v_mul_f32_e64 v14, v98, v14
	v_mul_f32_e64 v15, v99, v15
	v_mul_f32_e64 v12, v96, v12
	v_mul_f32_e64 v13, v97, v13
	s_waitcnt vmcnt(31)
	v_pk_mul_f32 v[10:11], v[182:183], v[10:11]
	v_pk_mul_f32 v[8:9], v[180:181], v[8:9]
	s_waitcnt vmcnt(29)
	v_pk_mul_f32 v[6:7], v[198:199], v[6:7]
	v_pk_mul_f32 v[4:5], v[196:197], v[4:5]
	s_waitcnt vmcnt(28)
	v_pk_mul_f32 v[2:3], v[202:203], v[2:3]
	v_pk_mul_f32 v[0:1], v[200:201], v[0:1]
	s_waitcnt vmcnt(26)
	v_mfma_f32_32x32x16_bf16 v[16:31], v[204:207], v[208:211], v[16:31]
	s_movk_i32 s14, 0x4000
	v_mfma_f32_32x32x16_bf16 v[0:15], v[192:195], v[92:95], v[0:15]
	s_waitcnt vmcnt(25)
	v_mfma_f32_32x32x16_bf16 v[0:15], v[32:35], v[208:211], v[0:15]
	s_waitcnt vmcnt(23)
	v_mfma_f32_32x32x16_bf16 v[16:31], v[40:43], v[212:215], v[16:31]
	global_load_dwordx4 v[56:59], v[224:225], off offset:3072
	global_load_dwordx4 v[40:43], v[226:227], off offset:-4096
	global_load_dwordx4 v[32:35], v[168:169], off offset:384
	s_waitcnt vmcnt(25)
	v_mfma_f32_32x32x16_bf16 v[0:15], v[216:219], v[212:215], v[0:15]
	s_waitcnt vmcnt(22)
	v_mfma_f32_32x32x16_bf16 v[16:31], v[48:51], v[116:119], v[16:31]
	global_load_dwordx4 v[92:95], v[174:175], off offset:64
	global_load_dwordx4 v[96:99], v[174:175], off offset:96
	global_load_dwordx4 v[84:87], v[174:175], off
	global_load_dwordx4 v[88:91], v[174:175], off offset:32
	global_load_dwordx4 v[80:83], v[176:177], off offset:32
	global_load_dwordx4 v[48:51], v[172:173], off offset:224
	s_waitcnt vmcnt(21)
	s_nop 4
	v_pk_mul_f32 v[30:31], v[150:151], v[30:31]
	v_mfma_f32_32x32x16_bf16 v[0:15], v[124:127], v[116:119], v[0:15]
	v_mul_f32_e64 v28, v148, v28
	v_mul_f32_e64 v29, v149, v29
	v_mul_f32_e64 v26, v146, v26
	v_mul_f32_e64 v27, v147, v27
	v_mul_f32_e64 v24, v144, v24
	v_mul_f32_e64 v25, v145, v25
	v_pk_mul_f32 v[22:23], v[138:139], v[22:23]
	v_pk_mul_f32 v[20:21], v[136:137], v[20:21]
	v_pk_mul_f32 v[18:19], v[130:131], v[18:19]
	v_pk_mul_f32 v[16:17], v[128:129], v[16:17]
	s_waitcnt vmcnt(17)
	s_nop 0
	v_pk_mul_f32 v[14:15], v[142:143], v[14:15]
	v_pk_mul_f32 v[12:13], v[140:141], v[12:13]
	v_mfma_f32_32x32x16_bf16 v[16:31], v[108:111], v[104:107], v[16:31]
	v_mul_f32_e64 v10, v134, v10
	v_mul_f32_e64 v11, v135, v11
	v_mul_f32_e64 v8, v132, v8
	v_mul_f32_e64 v9, v133, v9
	v_mul_f32_e64 v6, v122, v6
	v_mul_f32_e64 v7, v123, v7
	v_pk_mul_f32 v[4:5], v[120:121], v[4:5]
	v_pk_mul_f32 v[2:3], v[114:115], v[2:3]
	v_pk_mul_f32 v[0:1], v[112:113], v[0:1]
	v_add_co_u32_e32 v140, vcc, s14, v170
	s_nop 0
	v_mfma_f32_32x32x16_bf16 v[0:15], v[100:103], v[104:107], v[0:15]
	global_load_dwordx4 v[100:103], v[226:227], off offset:-3072
	global_load_dwordx4 v[104:107], v[168:169], off offset:416
	v_addc_co_u32_e32 v141, vcc, 0, v171, vcc
	s_movk_i32 s14, 0x5000
	s_waitcnt vmcnt(17)
	v_mfma_f32_32x32x16_bf16 v[16:31], v[36:39], v[72:75], v[16:31]
	global_load_dwordx4 v[36:39], v[226:227], off offset:-2048
	global_load_dwordx4 v[108:111], v[168:169], off offset:448
	s_waitcnt vmcnt(16)
	v_mfma_f32_32x32x16_bf16 v[16:31], v[68:71], v[52:55], v[16:31]
	v_mfma_f32_32x32x16_bf16 v[0:15], v[76:79], v[72:75], v[0:15]
	global_load_dwordx4 v[72:75], v[226:227], off offset:-1024
	global_load_dwordx4 v[76:79], v[168:169], off offset:480
	global_load_dwordx4 v[112:115], v[174:175], off offset:224
	global_load_dwordx4 v[116:119], v[174:175], off offset:192
	global_load_dwordx4 v[120:123], v[174:175], off offset:160
	global_load_dwordx4 v[68:71], v[226:227], off
	global_load_dwordx4 v[124:127], v[174:175], off offset:128
	s_waitcnt vmcnt(21)
	v_mfma_f32_32x32x16_bf16 v[16:31], v[64:67], v[44:47], v[16:31]
	global_load_dwordx4 v[64:67], v[226:227], off offset:1024
	s_waitcnt vmcnt(21)
	v_mfma_f32_32x32x16_bf16 v[0:15], v[60:63], v[52:55], v[0:15]
	global_load_dwordx4 v[52:55], v[226:227], off offset:2048
	global_load_dwordx4 v[60:63], v[226:227], off offset:3072
	s_waitcnt vmcnt(19)
	s_nop 5
	v_mul_f32_e64 v26, v94, v26
	v_mul_f32_e64 v27, v95, v27
	v_mfma_f32_32x32x16_bf16 v[0:15], v[56:59], v[44:47], v[0:15]
	global_load_dwordx4 v[44:47], v[228:229], off offset:-4096
	s_waitcnt vmcnt(19)
	v_mul_f32_e64 v30, v98, v30
	v_mul_f32_e64 v31, v99, v31
	v_mul_f32_e64 v28, v96, v28
	v_mul_f32_e64 v29, v97, v29
	v_pk_mul_f32 v[24:25], v[92:93], v[24:25]
	global_load_dwordx4 v[56:59], v[176:177], off offset:64
	global_load_dwordx4 v[92:95], v[176:177], off offset:96
	s_waitcnt vmcnt(19)
	v_pk_mul_f32 v[22:23], v[90:91], v[22:23]
	v_pk_mul_f32 v[20:21], v[88:89], v[20:21]
	global_load_dwordx4 v[88:91], v[140:141], off offset:-4096
	v_pk_mul_f32 v[18:19], v[86:87], v[18:19]
	v_pk_mul_f32 v[16:17], v[84:85], v[16:17]
	s_waitcnt vmcnt(11)
	v_pk_mul_f32 v[14:15], v[114:115], v[14:15]
	v_mfma_f32_32x32x16_bf16 v[16:31], v[40:43], v[32:35], v[16:31]
	global_load_dwordx4 v[40:43], v[168:169], off offset:512
	global_load_dwordx4 v[84:87], v[228:229], off offset:-3072
	global_load_dwordx4 v[96:99], v[168:169], off offset:544
	v_mul_f32_e64 v12, v112, v12
	v_mul_f32_e64 v13, v113, v13
	s_waitcnt vmcnt(13)
	v_pk_mul_f32 v[10:11], v[118:119], v[10:11]
	v_pk_mul_f32 v[8:9], v[116:117], v[8:9]
	s_waitcnt vmcnt(12)
	v_pk_mul_f32 v[6:7], v[122:123], v[6:7]
	v_pk_mul_f32 v[4:5], v[120:121], v[4:5]
	v_mfma_f32_32x32x16_bf16 v[16:31], v[100:103], v[104:107], v[16:31]
	s_waitcnt vmcnt(10)
	v_mul_f32_e64 v2, v126, v2
	v_mul_f32_e64 v3, v127, v3
	v_mul_f32_e64 v0, v124, v0
	v_mul_f32_e64 v1, v125, v1
	v_mfma_f32_32x32x16_bf16 v[16:31], v[36:39], v[108:111], v[16:31]
	global_load_dwordx4 v[36:39], v[228:229], off offset:-2048
	global_load_dwordx4 v[100:103], v[168:169], off offset:576
	global_load_dwordx4 v[128:131], v[228:229], off offset:-1024
	global_load_dwordx4 v[132:135], v[168:169], off offset:608
	global_load_dwordx4 v[136:139], v[228:229], off
	v_mfma_f32_32x32x16_bf16 v[0:15], v[68:71], v[32:35], v[0:15]
	v_mfma_f32_32x32x16_bf16 v[16:31], v[72:75], v[76:79], v[16:31]
	global_load_dwordx4 v[72:75], v[176:177], off offset:192
	global_load_dwordx4 v[112:115], v[176:177], off offset:224
	global_load_dwordx4 v[32:35], v[176:177], off offset:160
	global_load_dwordx4 v[68:71], v[176:177], off offset:128
	s_waitcnt vmcnt(18)
	v_mfma_f32_32x32x16_bf16 v[0:15], v[64:67], v[104:107], v[0:15]
	global_load_dwordx4 v[64:67], v[228:229], off offset:1024
	s_waitcnt vmcnt(14)
	s_nop 3
	v_mul_f32_e64 v30, v94, v30
	v_mul_f32_e64 v31, v95, v31
	v_mul_f32_e64 v28, v92, v28
	v_mul_f32_e64 v29, v93, v29
	v_pk_mul_f32 v[26:27], v[58:59], v[26:27]
	v_pk_mul_f32 v[24:25], v[56:57], v[24:25]
	v_pk_mul_f32 v[22:23], v[82:83], v[22:23]
	v_pk_mul_f32 v[20:21], v[80:81], v[20:21]
	v_mfma_f32_32x32x16_bf16 v[0:15], v[52:55], v[108:111], v[0:15]
	global_load_dwordx4 v[52:55], v[228:229], off offset:2048
	global_load_dwordx4 v[104:107], v[228:229], off offset:3072
	s_waitcnt vmcnt(15)
	v_mul_f32_e64 v18, v90, v18
	v_mul_f32_e64 v19, v91, v19
	v_pk_mul_f32 v[16:17], v[88:89], v[16:17]
	global_load_dwordx4 v[56:59], v[140:141], off
	s_waitcnt vmcnt(15)
	v_mfma_f32_32x32x16_bf16 v[16:31], v[44:47], v[40:43], v[16:31]
	v_mfma_f32_32x32x16_bf16 v[0:15], v[60:63], v[76:79], v[0:15]
	global_load_dwordx4 v[60:63], v[140:141], off offset:96
	global_load_dwordx4 v[76:79], v[140:141], off offset:64
	global_load_dwordx4 v[44:47], v[140:141], off offset:32
	global_load_dwordx4 v[80:83], v[230:231], off offset:-4096
	s_waitcnt vmcnt(17)
	v_mfma_f32_32x32x16_bf16 v[16:31], v[84:87], v[96:99], v[16:31]
	global_load_dwordx4 v[84:87], v[168:169], off offset:640
	global_load_dwordx4 v[88:91], v[230:231], off offset:-3072
	s_waitcnt vmcnt(13)
	s_nop 2
	v_mul_f32_e64 v10, v74, v10
	v_mul_f32_e64 v11, v75, v11
	v_mfma_f32_32x32x16_bf16 v[16:31], v[36:39], v[100:103], v[16:31]
	global_load_dwordx4 v[36:39], v[168:169], off offset:672
	global_load_dwordx4 v[92:95], v[230:231], off offset:-2048
	global_load_dwordx4 v[108:111], v[168:169], off offset:704
	global_load_dwordx4 v[116:119], v[230:231], off offset:-1024
	s_waitcnt vmcnt(16)
	v_pk_mul_f32 v[14:15], v[114:115], v[14:15]
	v_pk_mul_f32 v[12:13], v[112:113], v[12:13]
	v_pk_mul_f32 v[8:9], v[72:73], v[8:9]
	s_waitcnt vmcnt(15)
	v_pk_mul_f32 v[6:7], v[34:35], v[6:7]
	v_pk_mul_f32 v[4:5], v[32:33], v[4:5]
	s_waitcnt vmcnt(14)
	v_pk_mul_f32 v[2:3], v[70:71], v[2:3]
	v_pk_mul_f32 v[0:1], v[68:69], v[0:1]
	v_mfma_f32_32x32x16_bf16 v[16:31], v[128:131], v[132:135], v[16:31]
	s_nop 0
	v_mfma_f32_32x32x16_bf16 v[0:15], v[136:139], v[40:43], v[0:15]
	global_load_dwordx4 v[32:35], v[168:169], off offset:736
	global_load_dwordx4 v[40:43], v[140:141], off offset:224
	global_load_dwordx4 v[68:71], v[140:141], off offset:192
	global_load_dwordx4 v[72:75], v[140:141], off offset:160
	s_waitcnt vmcnt(14)
	s_nop 4
	v_pk_mul_f32 v[18:19], v[58:59], v[18:19]
	v_pk_mul_f32 v[16:17], v[56:57], v[16:17]
	s_waitcnt vmcnt(13)
	v_pk_mul_f32 v[30:31], v[62:63], v[30:31]
	v_mfma_f32_32x32x16_bf16 v[0:15], v[64:67], v[96:99], v[0:15]
	global_load_dwordx4 v[64:67], v[230:231], off
	global_load_dwordx4 v[96:99], v[140:141], off offset:128
	v_add_co_u32_e32 v140, vcc, s14, v170
	s_movk_i32 s14, 0x6000
	s_nop 0
	v_addc_co_u32_e32 v141, vcc, 0, v171, vcc
	v_add_co_u32_e32 v142, vcc, s14, v170
	v_mfma_f32_32x32x16_bf16 v[0:15], v[52:55], v[100:103], v[0:15]
	global_load_dwordx4 v[52:55], v[230:231], off offset:1024
	global_load_dwordx4 v[100:103], v[230:231], off offset:2048
	global_load_dwordx4 v[112:115], v[230:231], off offset:3072
	v_addc_co_u32_e32 v143, vcc, 0, v171, vcc
	v_mul_f32_e64 v28, v60, v28
	v_mul_f32_e64 v29, v61, v29
	s_waitcnt vmcnt(17)
	v_pk_mul_f32 v[26:27], v[78:79], v[26:27]
	v_pk_mul_f32 v[24:25], v[76:77], v[24:25]
	s_waitcnt vmcnt(16)
	v_pk_mul_f32 v[22:23], v[46:47], v[22:23]
	v_mfma_f32_32x32x16_bf16 v[0:15], v[104:107], v[132:135], v[0:15]
	global_load_dwordx4 v[104:107], v[232:233], off offset:-4096
	v_mul_f32_e64 v20, v44, v20
	v_mul_f32_e64 v21, v45, v21
	global_load_dwordx4 v[44:47], v[140:141], off offset:96
	global_load_dwordx4 v[56:59], v[140:141], off offset:32
	global_load_dwordx4 v[60:63], v[140:141], off offset:64
	global_load_dwordx4 v[76:79], v[142:143], off offset:-4096
	s_movk_i32 s14, 0x7000
	v_add_co_u32_e32 v174, vcc, s14, v170
	s_waitcnt vmcnt(19)
	v_mfma_f32_32x32x16_bf16 v[16:31], v[80:83], v[84:87], v[16:31]
	global_load_dwordx4 v[80:83], v[168:169], off offset:768
	global_load_dwordx4 v[120:123], v[232:233], off offset:-3072
	v_addc_co_u32_e32 v175, vcc, 0, v171, vcc
	s_mov_b32 s14, 0x8000
	v_add_co_u32_e32 v176, vcc, s14, v170
	s_mov_b32 s14, 0x9000
	s_waitcnt vmcnt(19)
	v_mfma_f32_32x32x16_bf16 v[16:31], v[88:91], v[36:39], v[16:31]
	global_load_dwordx4 v[88:91], v[168:169], off offset:800
	global_load_dwordx4 v[124:127], v[232:233], off offset:-2048
	v_addc_co_u32_e32 v177, vcc, 0, v171, vcc
	s_waitcnt vmcnt(16)
	v_mul_f32_e64 v14, v42, v14
	v_mul_f32_e64 v15, v43, v15
	v_pk_mul_f32 v[12:13], v[40:41], v[12:13]
	s_waitcnt vmcnt(15)
	v_pk_mul_f32 v[10:11], v[70:71], v[10:11]
	v_mfma_f32_32x32x16_bf16 v[16:31], v[92:95], v[108:111], v[16:31]
	v_mul_f32_e64 v8, v68, v8
	v_mul_f32_e64 v9, v69, v9
	s_waitcnt vmcnt(14)
	v_mul_f32_e64 v6, v74, v6
	v_mul_f32_e64 v7, v75, v7
	v_pk_mul_f32 v[4:5], v[72:73], v[4:5]
	global_load_dwordx4 v[92:95], v[168:169], off offset:832
	global_load_dwordx4 v[128:131], v[232:233], off offset:-1024
	global_load_dwordx4 v[132:135], v[168:169], off offset:864
	global_load_dwordx4 v[136:139], v[232:233], off
	s_waitcnt vmcnt(16)
	v_pk_mul_f32 v[2:3], v[98:99], v[2:3]
	v_pk_mul_f32 v[0:1], v[96:97], v[0:1]
	v_mfma_f32_32x32x16_bf16 v[16:31], v[116:119], v[32:35], v[16:31]
	global_load_dwordx4 v[40:43], v[140:141], off offset:224
	global_load_dwordx4 v[68:71], v[140:141], off offset:160
	global_load_dwordx4 v[116:119], v[140:141], off offset:192
	v_mfma_f32_32x32x16_bf16 v[0:15], v[64:67], v[84:87], v[0:15]
	global_load_dwordx4 v[64:67], v[140:141], off offset:128
	s_waitcnt vmcnt(15)
	s_nop 5
	v_mul_f32_e64 v30, v46, v30
	v_mul_f32_e64 v31, v47, v31
	v_mfma_f32_32x32x16_bf16 v[0:15], v[52:55], v[36:39], v[0:15]
	global_load_dwordx4 v[36:39], v[232:233], off offset:1024
	global_load_dwordx4 v[52:55], v[232:233], off offset:2048
	global_load_dwordx4 v[72:75], v[232:233], off offset:3072
	v_mul_f32_e64 v28, v44, v28
	v_mul_f32_e64 v29, v45, v29
	s_waitcnt vmcnt(16)
	v_pk_mul_f32 v[26:27], v[62:63], v[26:27]
	v_pk_mul_f32 v[24:25], v[60:61], v[24:25]
	v_pk_mul_f32 v[22:23], v[58:59], v[22:23]
	v_pk_mul_f32 v[20:21], v[56:57], v[20:21]
	v_mfma_f32_32x32x16_bf16 v[0:15], v[100:103], v[108:111], v[0:15]
	s_waitcnt vmcnt(15)
	v_mul_f32_e64 v18, v78, v18
	v_mul_f32_e64 v19, v79, v19
	v_mul_f32_e64 v16, v76, v16
	v_mul_f32_e64 v17, v77, v17
	v_mfma_f32_32x32x16_bf16 v[0:15], v[112:115], v[32:35], v[0:15]
	global_load_dwordx4 v[32:35], v[142:143], off offset:96
	global_load_dwordx4 v[44:47], v[142:143], off offset:64
	global_load_dwordx4 v[56:59], v[234:235], off offset:-4096
	global_load_dwordx4 v[60:63], v[142:143], off offset:32
	global_load_dwordx4 v[76:79], v[142:143], off
	global_load_dwordx4 v[84:87], v[168:169], off offset:896
	global_load_dwordx4 v[96:99], v[234:235], off offset:-3072
	s_waitcnt vmcnt(13)
	s_nop 3
	v_pk_mul_f32 v[14:15], v[42:43], v[14:15]
	v_mfma_f32_32x32x16_bf16 v[16:31], v[104:107], v[80:83], v[16:31]
	v_mul_f32_e64 v12, v40, v12
	v_mul_f32_e64 v13, v41, v13
	s_waitcnt vmcnt(11)
	v_mul_f32_e64 v10, v118, v10
	v_mul_f32_e64 v11, v119, v11
	v_pk_mul_f32 v[8:9], v[116:117], v[8:9]
	v_pk_mul_f32 v[6:7], v[70:71], v[6:7]
	v_pk_mul_f32 v[4:5], v[68:69], v[4:5]
	s_waitcnt vmcnt(10)
	v_pk_mul_f32 v[2:3], v[66:67], v[2:3]
	v_mfma_f32_32x32x16_bf16 v[16:31], v[120:123], v[88:91], v[16:31]
	global_load_dwordx4 v[100:103], v[168:169], off offset:928
	global_load_dwordx4 v[104:107], v[234:235], off offset:-2048
	global_load_dwordx4 v[108:111], v[168:169], off offset:960
	global_load_dwordx4 v[112:115], v[168:169], off offset:992
	global_load_dwordx4 v[120:123], v[234:235], off offset:-1024
	v_pk_mul_f32 v[0:1], v[64:65], v[0:1]
	s_nop 1
	v_mfma_f32_32x32x16_bf16 v[0:15], v[136:139], v[80:83], v[0:15]
	v_mfma_f32_32x32x16_bf16 v[16:31], v[124:127], v[92:95], v[16:31]
	global_load_dwordx4 v[124:127], v[174:175], off offset:32
	global_load_dwordx4 v[40:43], v[142:143], off offset:192
	global_load_dwordx4 v[116:119], v[142:143], off offset:224
	global_load_dwordx4 v[64:67], v[142:143], off offset:160
	global_load_dwordx4 v[68:71], v[234:235], off
	global_load_dwordx4 v[80:83], v[142:143], off offset:128
	s_waitcnt vmcnt(20)
	v_mfma_f32_32x32x16_bf16 v[0:15], v[36:39], v[88:91], v[0:15]
	global_load_dwordx4 v[88:91], v[234:235], off offset:1024
	s_waitcnt vmcnt(20)
	v_mfma_f32_32x32x16_bf16 v[0:15], v[52:55], v[92:95], v[0:15]
	global_load_dwordx4 v[52:55], v[234:235], off offset:2048
	global_load_dwordx4 v[92:95], v[234:235], off offset:3072
	v_mfma_f32_32x32x16_bf16 v[16:31], v[128:131], v[132:135], v[16:31]
	s_waitcnt vmcnt(21)
	v_mfma_f32_32x32x16_bf16 v[0:15], v[72:75], v[132:135], v[0:15]
	s_waitcnt vmcnt(20)
	s_nop 8
	v_mul_f32_e64 v30, v34, v30
	v_mul_f32_e64 v31, v35, v31
	v_mul_f32_e64 v28, v32, v28
	v_mul_f32_e64 v29, v33, v29
	s_waitcnt vmcnt(19)
	v_pk_mul_f32 v[26:27], v[46:47], v[26:27]
	v_pk_mul_f32 v[24:25], v[44:45], v[24:25]
	s_waitcnt vmcnt(17)
	v_pk_mul_f32 v[22:23], v[62:63], v[22:23]
	v_pk_mul_f32 v[20:21], v[60:61], v[20:21]
	s_waitcnt vmcnt(16)
	v_pk_mul_f32 v[18:19], v[78:79], v[18:19]
	v_pk_mul_f32 v[16:17], v[76:77], v[16:17]
	s_waitcnt vmcnt(7)
	v_pk_mul_f32 v[42:43], v[42:43], v[10:11]
	v_mfma_f32_32x32x16_bf16 v[16:31], v[56:59], v[84:87], v[16:31]
	global_load_dwordx4 v[56:59], v[174:175], off offset:96
	global_load_dwordx4 v[60:63], v[174:175], off offset:64
	global_load_dwordx4 v[72:75], v[236:237], off offset:-4096
	global_load_dwordx4 v[76:79], v[176:177], off offset:-4096
	s_waitcnt vmcnt(10)
	v_pk_mul_f32 v[46:47], v[118:119], v[14:15]
	v_pk_mul_f32 v[44:45], v[116:117], v[12:13]
	v_pk_mul_f32 v[40:41], v[40:41], v[8:9]
	s_waitcnt vmcnt(9)
	v_pk_mul_f32 v[38:39], v[66:67], v[6:7]
	v_pk_mul_f32 v[36:37], v[64:65], v[4:5]
	v_mfma_f32_32x32x16_bf16 v[16:31], v[96:99], v[100:103], v[16:31]
	global_load_dwordx4 v[96:99], v[168:169], off offset:1024
	global_load_dwordx4 v[128:131], v[236:237], off offset:-3072
	s_waitcnt vmcnt(9)
	v_mul_f32_e64 v34, v82, v2
	v_mul_f32_e64 v35, v83, v3
	v_pk_mul_f32 v[32:33], v[80:81], v[0:1]
	s_nop 1
	v_mfma_f32_32x32x16_bf16 v[32:47], v[68:71], v[84:87], v[32:47]
	v_mfma_f32_32x32x16_bf16 v[16:31], v[104:107], v[108:111], v[16:31]
	global_load_dwordx4 v[104:107], v[168:169], off offset:1056
	global_load_dwordx4 v[132:135], v[236:237], off offset:-2048
	global_load_dwordx4 v[136:139], v[236:237], off offset:-1024
	global_load_dwordx4 v[140:143], v[236:237], off
	global_load_dwordx4 v[144:147], v[168:169], off offset:1120
	global_load_dwordx4 v[148:151], v[168:169], off offset:1088
	global_load_dwordx4 v[64:67], v[174:175], off offset:192
	global_load_dwordx4 v[116:119], v[174:175], off offset:224
	global_load_dwordx4 v[68:71], v[174:175], off offset:160
	global_load_dwordx4 v[80:83], v[174:175], off offset:128
	global_load_dwordx4 v[84:87], v[236:237], off offset:1024
	s_waitcnt vmcnt(19)
	v_mfma_f32_32x32x16_bf16 v[32:47], v[88:91], v[100:103], v[32:47]
	s_waitcnt vmcnt(18)
	v_mfma_f32_32x32x16_bf16 v[32:47], v[52:55], v[108:111], v[32:47]
	global_load_dwordx4 v[52:55], v[236:237], off offset:2048
	v_mfma_f32_32x32x16_bf16 v[16:31], v[120:123], v[112:115], v[16:31]
	s_waitcnt vmcnt(18)
	v_mfma_f32_32x32x16_bf16 v[32:47], v[92:95], v[112:115], v[32:47]
	s_nop 9
	v_mul_f32_e64 v6, v126, v22
	v_mul_f32_e64 v7, v127, v23
	v_mul_f32_e64 v4, v124, v20
	v_mul_f32_e64 v5, v125, v21
	v_add_co_u32_e32 v124, vcc, s14, v170
	s_mov_b32 s14, 0xa000
	s_nop 0
	v_addc_co_u32_e32 v125, vcc, 0, v171, vcc
	v_add_co_u32_e32 v126, vcc, s14, v170
	s_mov_b32 s14, 0xb000
	s_nop 0
	v_addc_co_u32_e32 v127, vcc, 0, v171, vcc
	s_waitcnt vmcnt(17)
	v_pk_mul_f32 v[14:15], v[58:59], v[30:31]
	v_pk_mul_f32 v[12:13], v[56:57], v[28:29]
	global_load_dwordx4 v[56:59], v[176:177], off
	s_waitcnt vmcnt(17)
	v_pk_mul_f32 v[10:11], v[62:63], v[26:27]
	v_pk_mul_f32 v[8:9], v[60:61], v[24:25]
	s_waitcnt vmcnt(15)
	v_pk_mul_f32 v[2:3], v[78:79], v[18:19]
	v_pk_mul_f32 v[0:1], v[76:77], v[16:17]
	s_waitcnt vmcnt(6)
	v_pk_mul_f32 v[26:27], v[66:67], v[42:43]
	v_mfma_f32_32x32x16_bf16 v[0:15], v[72:75], v[96:99], v[0:15]
	global_load_dwordx4 v[60:63], v[236:237], off offset:3072
	global_load_dwordx4 v[72:75], v[176:177], off offset:96
	global_load_dwordx4 v[76:79], v[176:177], off offset:32
	global_load_dwordx4 v[88:91], v[176:177], off offset:64
	s_waitcnt vmcnt(9)
	v_pk_mul_f32 v[30:31], v[118:119], v[46:47]
	v_pk_mul_f32 v[28:29], v[116:117], v[44:45]
	v_pk_mul_f32 v[24:25], v[64:65], v[40:41]
	s_waitcnt vmcnt(8)
	v_pk_mul_f32 v[22:23], v[70:71], v[38:39]
	v_pk_mul_f32 v[20:21], v[68:69], v[36:37]
	s_waitcnt vmcnt(7)
	v_pk_mul_f32 v[18:19], v[82:83], v[34:35]
	v_pk_mul_f32 v[16:17], v[80:81], v[32:33]
	global_load_dwordx4 v[92:95], v[238:239], off offset:-4096
	global_load_dwordx4 v[100:103], v[168:169], off offset:1152
	v_mfma_f32_32x32x16_bf16 v[16:31], v[140:143], v[96:99], v[16:31]
	global_load_dwordx4 v[108:111], v[238:239], off offset:-3072
	global_load_dwordx4 v[112:115], v[168:169], off offset:1184
	global_load_dwordx4 v[120:123], v[238:239], off offset:-2048
	global_load_dwordx4 v[32:35], v[168:169], off offset:1216
	global_load_dwordx4 v[36:39], v[238:239], off offset:-1024
	global_load_dwordx4 v[40:43], v[168:169], off offset:1248
	global_load_dwordx4 v[44:47], v[176:177], off offset:224
	global_load_dwordx4 v[64:67], v[176:177], off offset:192
	global_load_dwordx4 v[68:71], v[176:177], off offset:160
	global_load_dwordx4 v[80:83], v[238:239], off
	s_waitcnt vmcnt(18)
	v_mfma_f32_32x32x16_bf16 v[16:31], v[84:87], v[104:107], v[16:31]
	v_mfma_f32_32x32x16_bf16 v[0:15], v[128:131], v[104:107], v[0:15]
	s_waitcnt vmcnt(17)
	v_mfma_f32_32x32x16_bf16 v[16:31], v[52:55], v[148:151], v[16:31]
	global_load_dwordx4 v[52:55], v[176:177], off offset:128
	global_load_dwordx4 v[84:87], v[238:239], off offset:1024
	v_mfma_f32_32x32x16_bf16 v[0:15], v[132:135], v[148:151], v[0:15]
	v_mfma_f32_32x32x16_bf16 v[0:15], v[136:139], v[144:147], v[0:15]
	s_waitcnt vmcnt(17)
	v_mfma_f32_32x32x16_bf16 v[16:31], v[60:63], v[144:147], v[16:31]
	s_waitcnt vmcnt(16)
	s_nop 8
	v_mul_f32_e64 v14, v74, v14
	v_mul_f32_e64 v15, v75, v15
	v_mul_f32_e64 v12, v72, v12
	v_mul_f32_e64 v13, v73, v13
	v_pk_mul_f32 v[2:3], v[58:59], v[2:3]
	v_pk_mul_f32 v[0:1], v[56:57], v[0:1]
	global_load_dwordx4 v[56:59], v[238:239], off offset:2048
	global_load_dwordx4 v[60:63], v[238:239], off offset:3072
	global_load_dwordx4 v[72:75], v[240:241], off offset:-4096
	s_waitcnt vmcnt(17)
	v_pk_mul_f32 v[10:11], v[90:91], v[10:11]
	v_pk_mul_f32 v[8:9], v[88:89], v[8:9]
	v_pk_mul_f32 v[6:7], v[78:79], v[6:7]
	v_pk_mul_f32 v[4:5], v[76:77], v[4:5]
	s_waitcnt vmcnt(8)
	v_pk_mul_f32 v[30:31], v[46:47], v[30:31]
	v_mfma_f32_32x32x16_bf16 v[0:15], v[92:95], v[100:103], v[0:15]
	v_mul_f32_e64 v28, v44, v28
	v_mul_f32_e64 v29, v45, v29
	s_waitcnt vmcnt(7)
	v_mul_f32_e64 v26, v66, v26
	v_mul_f32_e64 v27, v67, v27
	v_pk_mul_f32 v[24:25], v[64:65], v[24:25]
	s_waitcnt vmcnt(6)
	v_pk_mul_f32 v[22:23], v[70:71], v[22:23]
	v_pk_mul_f32 v[20:21], v[68:69], v[20:21]
	global_load_dwordx4 v[76:79], v[124:125], off offset:96
	global_load_dwordx4 v[88:91], v[124:125], off offset:32
	global_load_dwordx4 v[92:95], v[124:125], off offset:64
	global_load_dwordx4 v[96:99], v[126:127], off offset:-4096
	v_mfma_f32_32x32x16_bf16 v[0:15], v[108:111], v[112:115], v[0:15]
	s_waitcnt vmcnt(8)
	v_mul_f32_e64 v18, v54, v18
	v_mul_f32_e64 v19, v55, v19
	v_mul_f32_e64 v16, v52, v16
	v_mul_f32_e64 v17, v53, v17
	v_mfma_f32_32x32x16_bf16 v[0:15], v[120:123], v[32:35], v[0:15]
	global_load_dwordx4 v[104:107], v[168:169], off offset:1280
	global_load_dwordx4 v[108:111], v[240:241], off offset:-3072
	global_load_dwordx4 v[116:119], v[168:169], off offset:1312
	global_load_dwordx4 v[120:123], v[240:241], off offset:-2048
	v_mfma_f32_32x32x16_bf16 v[16:31], v[80:83], v[100:103], v[16:31]
	s_waitcnt vmcnt(11)
	v_mfma_f32_32x32x16_bf16 v[16:31], v[84:87], v[112:115], v[16:31]
	v_mfma_f32_32x32x16_bf16 v[0:15], v[36:39], v[40:43], v[0:15]
	global_load_dwordx4 v[36:39], v[168:169], off offset:1344
	global_load_dwordx4 v[44:47], v[240:241], off offset:-1024
	global_load_dwordx4 v[52:55], v[168:169], off offset:1376
	global_load_dwordx4 v[64:67], v[124:125], off offset:224
	global_load_dwordx4 v[68:71], v[124:125], off offset:192
	global_load_dwordx4 v[80:83], v[124:125], off offset:160
	global_load_dwordx4 v[84:87], v[240:241], off
	s_waitcnt vmcnt(14)
	s_nop 3
	v_pk_mul_f32 v[14:15], v[78:79], v[14:15]
	v_mfma_f32_32x32x16_bf16 v[16:31], v[56:59], v[32:35], v[16:31]
	global_load_dwordx4 v[32:35], v[124:125], off offset:128
	global_load_dwordx4 v[56:59], v[240:241], off offset:1024
	v_mul_f32_e64 v12, v76, v12
	v_mul_f32_e64 v13, v77, v13
	s_waitcnt vmcnt(14)
	v_pk_mul_f32 v[10:11], v[94:95], v[10:11]
	v_pk_mul_f32 v[8:9], v[92:93], v[8:9]
	v_pk_mul_f32 v[6:7], v[90:91], v[6:7]
	v_pk_mul_f32 v[4:5], v[88:89], v[4:5]
	s_waitcnt vmcnt(13)
	v_pk_mul_f32 v[2:3], v[98:99], v[2:3]
	v_mfma_f32_32x32x16_bf16 v[16:31], v[60:63], v[40:43], v[16:31]
	global_load_dwordx4 v[40:43], v[240:241], off offset:2048
	global_load_dwordx4 v[60:63], v[240:241], off offset:3072
	v_mul_f32_e64 v0, v96, v0
	v_mul_f32_e64 v1, v97, v1
	s_waitcnt vmcnt(14)
	s_nop 0
	v_mfma_f32_32x32x16_bf16 v[0:15], v[72:75], v[104:107], v[0:15]
	global_load_dwordx4 v[72:75], v[126:127], off offset:96
	global_load_dwordx4 v[76:79], v[126:127], off offset:64
	global_load_dwordx4 v[88:91], v[244:245], off offset:-4096
	global_load_dwordx4 v[92:95], v[126:127], off offset:32
	global_load_dwordx4 v[96:99], v[126:127], off
	s_waitcnt vmcnt(12)
	v_pk_mul_f32 v[30:31], v[66:67], v[30:31]
	v_pk_mul_f32 v[28:29], v[64:65], v[28:29]
	s_waitcnt vmcnt(11)
	v_pk_mul_f32 v[26:27], v[70:71], v[26:27]
	v_pk_mul_f32 v[24:25], v[68:69], v[24:25]
	s_waitcnt vmcnt(10)
	v_pk_mul_f32 v[22:23], v[82:83], v[22:23]
	v_pk_mul_f32 v[20:21], v[80:81], v[20:21]
	v_mfma_f32_32x32x16_bf16 v[0:15], v[108:111], v[116:119], v[0:15]
	global_load_dwordx4 v[100:103], v[168:169], off offset:1408
	global_load_dwordx4 v[108:111], v[168:169], off offset:1440
	global_load_dwordx4 v[112:115], v[244:245], off offset:-3072
	s_waitcnt vmcnt(11)
	v_mul_f32_e64 v18, v34, v18
	v_mul_f32_e64 v19, v35, v19
	v_pk_mul_f32 v[16:17], v[32:33], v[16:17]
	v_mfma_f32_32x32x16_bf16 v[0:15], v[120:123], v[36:39], v[0:15]
	v_add_co_u32_e32 v120, vcc, s14, v170
	s_mov_b32 s14, 0xc000
	s_nop 0
	v_addc_co_u32_e32 v121, vcc, 0, v171, vcc
	v_add_co_u32_e32 v124, vcc, s14, v170
	v_mfma_f32_32x32x16_bf16 v[16:31], v[84:87], v[104:107], v[16:31]
	s_nop 0
	v_addc_co_u32_e32 v125, vcc, 0, v171, vcc
	s_mov_b32 s14, 0xd000
	s_waitcnt vmcnt(10)
	v_mfma_f32_32x32x16_bf16 v[16:31], v[56:59], v[116:119], v[16:31]
	v_mfma_f32_32x32x16_bf16 v[0:15], v[44:47], v[52:55], v[0:15]
	global_load_dwordx4 v[44:47], v[120:121], off offset:32
	global_load_dwordx4 v[32:35], v[244:245], off offset:-2048
	global_load_dwordx4 v[64:67], v[168:169], off offset:1472
	global_load_dwordx4 v[56:59], v[244:245], off offset:-1024
	global_load_dwordx4 v[68:71], v[168:169], off offset:1504
	global_load_dwordx4 v[80:83], v[126:127], off offset:224
	global_load_dwordx4 v[84:87], v[126:127], off offset:192
	global_load_dwordx4 v[104:107], v[244:245], off
	s_waitcnt vmcnt(15)
	s_nop 2
	v_pk_mul_f32 v[14:15], v[74:75], v[14:15]
	v_mfma_f32_32x32x16_bf16 v[16:31], v[40:43], v[36:39], v[16:31]
	global_load_dwordx4 v[36:39], v[126:127], off offset:160
	global_load_dwordx4 v[40:43], v[126:127], off offset:128
	global_load_dwordx4 v[116:119], v[244:245], off offset:1024
	v_mul_f32_e64 v12, v72, v12
	v_mul_f32_e64 v13, v73, v13
	s_waitcnt vmcnt(17)
	v_pk_mul_f32 v[10:11], v[78:79], v[10:11]
	v_pk_mul_f32 v[8:9], v[76:77], v[8:9]
	s_waitcnt vmcnt(15)
	v_pk_mul_f32 v[6:7], v[94:95], v[6:7]
	v_pk_mul_f32 v[4:5], v[92:93], v[4:5]
	s_waitcnt vmcnt(14)
	v_pk_mul_f32 v[2:3], v[98:99], v[2:3]
	v_mfma_f32_32x32x16_bf16 v[16:31], v[60:63], v[52:55], v[16:31]
	global_load_dwordx4 v[52:55], v[244:245], off offset:2048
	global_load_dwordx4 v[60:63], v[244:245], off offset:3072
	v_mul_f32_e64 v0, v96, v0
	v_mul_f32_e64 v1, v97, v1
	s_waitcnt vmcnt(15)
	s_nop 0
	v_mfma_f32_32x32x16_bf16 v[0:15], v[88:91], v[100:103], v[0:15]
	global_load_dwordx4 v[72:75], v[120:121], off offset:96
	global_load_dwordx4 v[76:79], v[120:121], off offset:64
	global_load_dwordx4 v[88:91], v[246:247], off offset:-4096
	global_load_dwordx4 v[92:95], v[124:125], off offset:-4096
	s_waitcnt vmcnt(11)
	v_pk_mul_f32 v[30:31], v[82:83], v[30:31]
	v_mfma_f32_32x32x16_bf16 v[0:15], v[112:115], v[108:111], v[0:15]
	v_mul_f32_e64 v28, v80, v28
	v_mul_f32_e64 v29, v81, v29
	s_waitcnt vmcnt(10)
	v_mul_f32_e64 v26, v86, v26
	v_mul_f32_e64 v27, v87, v27
	v_pk_mul_f32 v[24:25], v[84:85], v[24:25]
	s_waitcnt vmcnt(8)
	v_pk_mul_f32 v[22:23], v[38:39], v[22:23]
	v_pk_mul_f32 v[20:21], v[36:37], v[20:21]
	s_waitcnt vmcnt(7)
	v_pk_mul_f32 v[18:19], v[42:43], v[18:19]
	v_pk_mul_f32 v[16:17], v[40:41], v[16:17]
	v_mfma_f32_32x32x16_bf16 v[0:15], v[32:35], v[64:67], v[0:15]
	global_load_dwordx4 v[32:35], v[168:169], off offset:1536
	global_load_dwordx4 v[96:99], v[246:247], off offset:-3072
	global_load_dwordx4 v[112:115], v[168:169], off offset:1568
	global_load_dwordx4 v[36:39], v[246:247], off offset:-2048
	global_load_dwordx4 v[40:43], v[168:169], off offset:1600
	v_mfma_f32_32x32x16_bf16 v[16:31], v[104:107], v[100:103], v[16:31]
	s_waitcnt vmcnt(11)
	v_mfma_f32_32x32x16_bf16 v[16:31], v[116:119], v[108:111], v[16:31]
	v_mfma_f32_32x32x16_bf16 v[0:15], v[56:59], v[68:71], v[0:15]
	global_load_dwordx4 v[56:59], v[246:247], off offset:-1024
	global_load_dwordx4 v[80:83], v[120:121], off offset:224
	global_load_dwordx4 v[84:87], v[168:169], off offset:1632
	global_load_dwordx4 v[100:103], v[120:121], off offset:192
	global_load_dwordx4 v[104:107], v[246:247], off
	global_load_dwordx4 v[108:111], v[120:121], off offset:160
	s_nop 5
	v_pk_mul_f32 v[6:7], v[46:47], v[6:7]
	s_waitcnt vmcnt(16)
	v_mfma_f32_32x32x16_bf16 v[16:31], v[52:55], v[64:67], v[16:31]
	global_load_dwordx4 v[52:55], v[120:121], off offset:128
	global_load_dwordx4 v[64:67], v[246:247], off offset:1024
	v_mul_f32_e64 v4, v44, v4
	v_mul_f32_e64 v5, v45, v5
	global_load_dwordx4 v[44:47], v[124:125], off
	s_waitcnt vmcnt(17)
	v_pk_mul_f32 v[14:15], v[74:75], v[14:15]
	v_pk_mul_f32 v[12:13], v[72:73], v[12:13]
	s_waitcnt vmcnt(16)
	v_pk_mul_f32 v[10:11], v[78:79], v[10:11]
	v_pk_mul_f32 v[8:9], v[76:77], v[8:9]
	v_mfma_f32_32x32x16_bf16 v[16:31], v[60:63], v[68:71], v[16:31]
	global_load_dwordx4 v[60:63], v[246:247], off offset:2048
	global_load_dwordx4 v[68:71], v[246:247], off offset:3072
	s_waitcnt vmcnt(16)
	v_mul_f32_e64 v2, v94, v2
	v_mul_f32_e64 v3, v95, v3
	v_pk_mul_f32 v[0:1], v[92:93], v[0:1]
	s_waitcnt vmcnt(15)
	s_nop 0
	v_mfma_f32_32x32x16_bf16 v[0:15], v[88:91], v[32:35], v[0:15]
	global_load_dwordx4 v[72:75], v[124:125], off offset:96
	global_load_dwordx4 v[76:79], v[124:125], off offset:64
	global_load_dwordx4 v[88:91], v[124:125], off offset:32
	global_load_dwordx4 v[92:95], v[248:249], off offset:-4096
	s_waitcnt vmcnt(13)
	v_pk_mul_f32 v[30:31], v[82:83], v[30:31]
	v_mfma_f32_32x32x16_bf16 v[0:15], v[96:99], v[112:115], v[0:15]
	v_mul_f32_e64 v28, v80, v28
	v_mul_f32_e64 v29, v81, v29
	s_waitcnt vmcnt(11)
	v_mul_f32_e64 v26, v102, v26
	v_mul_f32_e64 v27, v103, v27
	v_pk_mul_f32 v[24:25], v[100:101], v[24:25]
	s_waitcnt vmcnt(9)
	v_pk_mul_f32 v[22:23], v[110:111], v[22:23]
	v_pk_mul_f32 v[20:21], v[108:109], v[20:21]
	s_waitcnt vmcnt(8)
	v_pk_mul_f32 v[18:19], v[54:55], v[18:19]
	v_pk_mul_f32 v[16:17], v[52:53], v[16:17]
	v_mfma_f32_32x32x16_bf16 v[0:15], v[36:39], v[40:43], v[0:15]
	global_load_dwordx4 v[36:39], v[168:169], off offset:1664
	global_load_dwordx4 v[96:99], v[168:169], off offset:1696
	global_load_dwordx4 v[116:119], v[248:249], off offset:-3072
	global_load_dwordx4 v[120:123], v[248:249], off offset:-2048
	v_mfma_f32_32x32x16_bf16 v[16:31], v[104:107], v[32:35], v[16:31]
	global_load_dwordx4 v[32:35], v[168:169], off offset:1728
	s_waitcnt vmcnt(12)
	v_mfma_f32_32x32x16_bf16 v[16:31], v[64:67], v[112:115], v[16:31]
	v_mfma_f32_32x32x16_bf16 v[0:15], v[56:59], v[84:87], v[0:15]
	global_load_dwordx4 v[52:55], v[248:249], off offset:-1024
	global_load_dwordx4 v[56:59], v[124:125], off offset:224
	global_load_dwordx4 v[64:67], v[168:169], off offset:1760
	global_load_dwordx4 v[80:83], v[124:125], off offset:192
	global_load_dwordx4 v[100:103], v[124:125], off offset:160
	global_load_dwordx4 v[104:107], v[248:249], off
	s_waitcnt vmcnt(17)
	s_nop 4
	v_pk_mul_f32 v[2:3], v[46:47], v[2:3]
	s_waitcnt vmcnt(16)
	v_mfma_f32_32x32x16_bf16 v[16:31], v[60:63], v[40:43], v[16:31]
	global_load_dwordx4 v[40:43], v[124:125], off offset:128
	global_load_dwordx4 v[60:63], v[248:249], off offset:1024
	global_load_dwordx4 v[108:111], v[248:249], off offset:2048
	v_mul_f32_e64 v0, v44, v0
	v_mul_f32_e64 v1, v45, v1
	v_add_co_u32_e32 v124, vcc, s14, v170
	s_mov_b32 s14, 0xe000
	s_nop 0
	v_addc_co_u32_e32 v125, vcc, 0, v171, vcc
	s_waitcnt vmcnt(18)
	v_mfma_f32_32x32x16_bf16 v[16:31], v[68:71], v[84:87], v[16:31]
	global_load_dwordx4 v[44:47], v[248:249], off offset:3072
	global_load_dwordx4 v[68:71], v[250:251], off offset:-4096
	s_waitcnt vmcnt(19)
	v_mul_f32_e64 v14, v74, v14
	v_mul_f32_e64 v15, v75, v15
	v_pk_mul_f32 v[12:13], v[72:73], v[12:13]
	s_waitcnt vmcnt(18)
	v_pk_mul_f32 v[10:11], v[78:79], v[10:11]
	v_pk_mul_f32 v[8:9], v[76:77], v[8:9]
	s_waitcnt vmcnt(17)
	v_pk_mul_f32 v[6:7], v[90:91], v[6:7]
	v_pk_mul_f32 v[4:5], v[88:89], v[4:5]
	v_add_co_u32_e32 v126, vcc, s14, v170
	s_waitcnt vmcnt(15)
	v_mfma_f32_32x32x16_bf16 v[0:15], v[92:95], v[36:39], v[0:15]
	v_addc_co_u32_e32 v127, vcc, 0, v171, vcc
	global_load_dwordx4 v[72:75], v[124:125], off offset:96
	global_load_dwordx4 v[76:79], v[124:125], off offset:32
	global_load_dwordx4 v[84:87], v[124:125], off offset:64
	global_load_dwordx4 v[88:91], v[126:127], off offset:-4096
	s_or_b32 s14, s1, s0
	s_ashr_i32 s15, s14, 31
	s_waitcnt vmcnt(17)
	v_mfma_f32_32x32x16_bf16 v[0:15], v[116:119], v[96:99], v[0:15]
	global_load_dwordx4 v[92:95], v[168:169], off offset:1792
	global_load_dwordx4 v[112:115], v[250:251], off offset:-3072
	global_load_dwordx4 v[116:119], v[168:169], off offset:1824
	s_lshl_b64 s[14:15], s[14:15], 15
	s_cmp_lg_u32 s0, 0
	s_waitcnt vmcnt(16)
	v_pk_mul_f32 v[30:31], v[58:59], v[30:31]
	v_pk_mul_f32 v[28:29], v[56:57], v[28:29]
	s_waitcnt vmcnt(14)
	v_pk_mul_f32 v[26:27], v[82:83], v[26:27]
	v_pk_mul_f32 v[24:25], v[80:81], v[24:25]
	s_waitcnt vmcnt(13)
	v_pk_mul_f32 v[22:23], v[102:103], v[22:23]
	v_pk_mul_f32 v[20:21], v[100:101], v[20:21]
	v_mfma_f32_32x32x16_bf16 v[0:15], v[120:123], v[32:35], v[0:15]
	s_waitcnt vmcnt(11)
	v_mul_f32_e64 v18, v42, v18
	v_mul_f32_e64 v19, v43, v19
	v_mul_f32_e64 v16, v40, v16
	v_mul_f32_e64 v17, v41, v17
	v_mfma_f32_32x32x16_bf16 v[0:15], v[52:55], v[64:67], v[0:15]
	s_nop 0
	v_mfma_f32_32x32x16_bf16 v[16:31], v[104:107], v[36:39], v[16:31]
	global_load_dwordx4 v[36:39], v[250:251], off offset:-2048
	global_load_dwordx4 v[40:43], v[168:169], off offset:1856
	global_load_dwordx4 v[52:55], v[250:251], off offset:-1024
	s_waitcnt vmcnt(9)
	s_nop 5
	v_mul_f32_e64 v14, v74, v14
	v_mul_f32_e64 v15, v75, v15
	v_mfma_f32_32x32x16_bf16 v[16:31], v[60:63], v[96:99], v[16:31]
	global_load_dwordx4 v[56:59], v[124:125], off offset:224
	global_load_dwordx4 v[60:63], v[168:169], off offset:1888
	global_load_dwordx4 v[80:83], v[124:125], off offset:192
	global_load_dwordx4 v[96:99], v[124:125], off offset:160
	global_load_dwordx4 v[100:103], v[250:251], off
	v_pk_mul_f32 v[12:13], v[72:73], v[12:13]
	s_waitcnt vmcnt(12)
	v_pk_mul_f32 v[10:11], v[86:87], v[10:11]
	v_pk_mul_f32 v[8:9], v[84:85], v[8:9]
	v_pk_mul_f32 v[6:7], v[78:79], v[6:7]
	v_pk_mul_f32 v[4:5], v[76:77], v[4:5]
	s_waitcnt vmcnt(11)
	v_pk_mul_f32 v[2:3], v[90:91], v[2:3]
	v_mfma_f32_32x32x16_bf16 v[16:31], v[108:111], v[32:35], v[16:31]
	global_load_dwordx4 v[32:35], v[124:125], off offset:128
	global_load_dwordx4 v[104:107], v[250:251], off offset:1024
	v_mul_f32_e64 v0, v88, v0
	v_mul_f32_e64 v1, v89, v1
	v_mfma_f32_32x32x16_bf16 v[16:31], v[44:47], v[64:67], v[16:31]
	global_load_dwordx4 v[44:47], v[250:251], off offset:2048
	global_load_dwordx4 v[64:67], v[250:251], off offset:3072
	s_waitcnt vmcnt(14)
	v_mfma_f32_32x32x16_bf16 v[0:15], v[68:71], v[92:95], v[0:15]
	global_load_dwordx4 v[68:71], v[126:127], off offset:96
	global_load_dwordx4 v[72:75], v[126:127], off offset:64
	global_load_dwordx4 v[76:79], v[252:253], off offset:-4096
	global_load_dwordx4 v[84:87], v[126:127], off offset:32
	global_load_dwordx4 v[88:91], v[126:127], off
	s_waitcnt vmcnt(13)
	s_nop 1
	v_pk_mul_f32 v[30:31], v[58:59], v[30:31]
	v_mfma_f32_32x32x16_bf16 v[0:15], v[112:115], v[116:119], v[0:15]
	v_mul_f32_e64 v28, v56, v28
	v_mul_f32_e64 v29, v57, v29
	s_waitcnt vmcnt(11)
	v_mul_f32_e64 v26, v82, v26
	v_mul_f32_e64 v27, v83, v27
	v_pk_mul_f32 v[24:25], v[80:81], v[24:25]
	s_waitcnt vmcnt(10)
	v_pk_mul_f32 v[22:23], v[98:99], v[22:23]
	v_pk_mul_f32 v[20:21], v[96:97], v[20:21]
	s_waitcnt vmcnt(8)
	v_pk_mul_f32 v[18:19], v[34:35], v[18:19]
	v_pk_mul_f32 v[16:17], v[32:33], v[16:17]
	v_mfma_f32_32x32x16_bf16 v[0:15], v[36:39], v[40:43], v[0:15]
	global_load_dwordx4 v[36:39], v[168:169], off offset:1920
	global_load_dwordx4 v[108:111], v[252:253], off offset:-3072
	global_load_dwordx4 v[112:115], v[168:169], off offset:1952
	global_load_dwordx4 v[120:123], v[172:173], off
	global_load_dwordx4 v[32:35], v[168:169], off offset:1984
	v_mfma_f32_32x32x16_bf16 v[16:31], v[100:103], v[92:95], v[16:31]
	s_waitcnt vmcnt(12)
	v_mfma_f32_32x32x16_bf16 v[16:31], v[104:107], v[116:119], v[16:31]
	v_mfma_f32_32x32x16_bf16 v[0:15], v[52:55], v[60:63], v[0:15]
	global_load_dwordx4 v[52:55], v[252:253], off offset:-2048
	global_load_dwordx4 v[56:59], v[252:253], off offset:-1024
	global_load_dwordx4 v[80:83], v[126:127], off offset:224
	global_load_dwordx4 v[92:95], v[168:169], off offset:2016
	global_load_dwordx4 v[96:99], v[126:127], off offset:192
	global_load_dwordx4 v[100:103], v[126:127], off offset:160
	global_load_dwordx4 v[104:107], v[252:253], off
	s_waitcnt vmcnt(16)
	s_nop 3
	v_pk_mul_f32 v[14:15], v[14:15], v[70:71]
	v_mfma_f32_32x32x16_bf16 v[16:31], v[44:47], v[40:43], v[16:31]
	global_load_dwordx4 v[40:43], v[126:127], off offset:128
	v_mul_f32_e64 v12, v12, v68
	v_mul_f32_e64 v13, v13, v69
	s_waitcnt vmcnt(16)
	v_mul_f32_e64 v10, v10, v74
	v_mul_f32_e64 v11, v11, v75
	v_pk_mul_f32 v[8:9], v[8:9], v[72:73]
	s_waitcnt vmcnt(14)
	v_pk_mul_f32 v[6:7], v[6:7], v[86:87]
	v_pk_mul_f32 v[4:5], v[4:5], v[84:85]
	s_waitcnt vmcnt(13)
	v_pk_mul_f32 v[2:3], v[2:3], v[90:91]
	v_mfma_f32_32x32x16_bf16 v[16:31], v[64:67], v[60:63], v[16:31]
	global_load_dwordx4 v[44:47], v[252:253], off offset:1024
	global_load_dwordx4 v[60:63], v[172:173], off offset:32
	v_mul_f32_e64 v0, v0, v88
	v_mul_f32_e64 v1, v1, v89
	global_load_dwordx4 v[64:67], v[252:253], off offset:2048
	global_load_dwordx4 v[68:71], v[172:173], off offset:64
	global_load_dwordx4 v[72:75], v[252:253], off offset:3072
	s_waitcnt vmcnt(10)
	s_nop 3
	v_pk_mul_f32 v[30:31], v[30:31], v[82:83]
	v_mfma_f32_32x32x16_bf16 v[0:15], v[76:79], v[36:39], v[0:15]
	v_mul_f32_e64 v28, v28, v80
	v_mul_f32_e64 v29, v29, v81
	s_waitcnt vmcnt(8)
	v_mul_f32_e64 v26, v26, v98
	v_mul_f32_e64 v27, v27, v99
	v_pk_mul_f32 v[24:25], v[24:25], v[96:97]
	s_waitcnt vmcnt(7)
	v_pk_mul_f32 v[22:23], v[22:23], v[102:103]
	v_pk_mul_f32 v[20:21], v[20:21], v[100:101]
	s_waitcnt vmcnt(5)
	v_pk_mul_f32 v[18:19], v[18:19], v[42:43]
	v_mfma_f32_32x32x16_bf16 v[0:15], v[108:111], v[112:115], v[0:15]
	v_mul_f32_e64 v16, v16, v40
	v_mul_f32_e64 v17, v17, v41
	v_mfma_f32_32x32x16_bf16 v[0:15], v[52:55], v[32:35], v[0:15]
	global_load_dwordx4 v[52:55], v[172:173], off offset:96
	global_load_dwordx4 v[76:79], v[172:173], off offset:128
	global_load_dwordx4 v[84:87], v[172:173], off offset:160
	v_mfma_f32_32x32x16_bf16 v[16:31], v[104:107], v[36:39], v[16:31]
	global_load_dwordx4 v[36:39], v[172:173], off offset:192
	s_waitcnt vmcnt(8)
	v_mfma_f32_32x32x16_bf16 v[16:31], v[44:47], v[112:115], v[16:31]
	s_waitcnt vmcnt(6)
	v_mfma_f32_32x32x16_bf16 v[16:31], v[64:67], v[32:35], v[16:31]
	v_mfma_f32_32x32x16_bf16 v[0:15], v[56:59], v[92:95], v[0:15]
	s_waitcnt vmcnt(4)
	v_mfma_f32_32x32x16_bf16 v[16:31], v[72:75], v[92:95], v[16:31]
	s_nop 9
	v_mul_f32_e32 v40, v120, v0
	v_mul_f32_e32 v41, v121, v1
	v_lshl_add_u64 v[0:1], v[156:157], 0, s[14:15]
	v_mul_f32_e32 v2, v122, v2
	v_mul_f32_e32 v3, v123, v3
	v_mul_f32_e32 v4, v60, v4
	v_mul_f32_e32 v5, v61, v5
	v_mul_f32_e32 v6, v62, v6
	v_mul_f32_e32 v7, v63, v7
	v_mul_f32_e32 v8, v68, v8
	v_mul_f32_e32 v9, v69, v9
	v_mul_f32_e32 v10, v70, v10
	v_mul_f32_e32 v11, v71, v11
	v_mul_f32_e32 v31, v51, v31
	v_mul_f32_e32 v28, v48, v28
	v_mul_f32_e32 v29, v49, v29
	v_mul_f32_e32 v30, v50, v30
	s_waitcnt vmcnt(3)
	v_mul_f32_e32 v12, v52, v12
	v_mul_f32_e32 v13, v53, v13
	v_mul_f32_e32 v14, v54, v14
	v_mul_f32_e32 v15, v55, v15
	global_store_dword v[0:1], v40, off
	global_store_dword v[0:1], v41, off offset:256
	global_store_dword v[0:1], v2, off offset:512
	global_store_dword v[0:1], v3, off offset:768
	global_store_dword v[0:1], v4, off offset:1024
	global_store_dword v[0:1], v5, off offset:1280
	global_store_dword v[0:1], v6, off offset:1536
	global_store_dword v[0:1], v7, off offset:1792
	global_store_dword v[0:1], v8, off offset:2048
	global_store_dword v[0:1], v9, off offset:2304
	global_store_dword v[0:1], v10, off offset:2560
	global_store_dword v[0:1], v11, off offset:2816
	global_store_dword v[0:1], v12, off offset:3072
	global_store_dword v[0:1], v13, off offset:3328
	global_store_dword v[0:1], v14, off offset:3584
	global_store_dword v[0:1], v15, off offset:3840
	v_add_co_u32_e32 v0, vcc, s29, v0
	s_waitcnt vmcnt(18)
	v_mul_f32_e32 v16, v76, v16
	v_addc_co_u32_e32 v1, vcc, 0, v1, vcc
	v_mul_f32_e32 v17, v77, v17
	v_mul_f32_e32 v18, v78, v18
	v_mul_f32_e32 v19, v79, v19
	s_waitcnt vmcnt(17)
	v_mul_f32_e32 v20, v84, v20
	v_mul_f32_e32 v21, v85, v21
	v_mul_f32_e32 v22, v86, v22
	v_mul_f32_e32 v23, v87, v23
	s_waitcnt vmcnt(16)
	v_mul_f32_e32 v24, v36, v24
	v_mul_f32_e32 v25, v37, v25
	v_mul_f32_e32 v26, v38, v26
	v_mul_f32_e32 v27, v39, v27
	global_store_dword v[0:1], v16, off
	global_store_dword v[0:1], v17, off offset:256
	global_store_dword v[0:1], v18, off offset:512
	global_store_dword v[0:1], v19, off offset:768
	global_store_dword v[0:1], v20, off offset:1024
	global_store_dword v[0:1], v21, off offset:1280
	global_store_dword v[0:1], v22, off offset:1536
	global_store_dword v[0:1], v23, off offset:1792
	global_store_dword v[0:1], v24, off offset:2048
	global_store_dword v[0:1], v25, off offset:2304
	global_store_dword v[0:1], v26, off offset:2560
	global_store_dword v[0:1], v27, off offset:2816
	global_store_dword v[0:1], v28, off offset:3072
	global_store_dword v[0:1], v29, off offset:3328
	global_store_dword v[0:1], v30, off offset:3584
	global_store_dword v[0:1], v31, off offset:3840
	s_cbranch_scc1 .LBB0_209
	s_lshr_b32 s0, s6, 4
	s_and_b32 s0, s0, 3
	s_lshl_b32 s0, s0, 10
	s_add_u32 s0, s8, s0
	s_addc_u32 s1, s9, 0
	v_lshl_add_u64 v[0:1], v[158:159], 0, s[0:1]
	v_mov_b32_e32 v2, 1.0
	s_mov_b64 s[0:1], 0

.LBB0_214:
	v_mov_b32_e32 v188, 0x358637bd
	v_mov_b64_e32 v[190:191], 0x3d81000
	v_mov_b32_e32 v222, 0x1000
	v_mov_b32_e32 v223, 0x2000
	v_mov_b32_e32 v224, 0xff03000
	v_mov_b32_e32 v225, 1
	v_mbcnt_lo_u32_b32 v226, -1, 0
	v_mbcnt_hi_u32_b32 v226, -1, v226
	v_and_b32_e32 v227, 64, v226
	v_add_u32_e32 v227, 64, v227
	v_xor_b32_e32 v228, 32, v226
	v_xor_b32_e32 v229, 16, v226
	v_xor_b32_e32 v230, 8, v226
	v_xor_b32_e32 v231, 4, v226
	v_xor_b32_e32 v232, 2, v226
	v_xor_b32_e32 v233, 1, v226
	v_mov_b32_e32 v234, 0xff800000
	v_mov_b32_e32 v235, 0x10000
	v_mov_b32_e32 v236, 0x41b17218
	s_mov_b64 s[0:1], 0

.LBB0_223:
	s_lshl_b32 s0, s2, 4
	s_and_b32 s72, s0, 0xffffffc0
	s_ashr_i32 s73, s72, 31
	s_lshl_b64 s[0:1], s[72:73], 6
	v_lshl_add_u64 v[0:1], v[18:19], 0, s[0:1]
	s_barrier
	global_load_dwordx4 v[0:3], v[0:1], off
	s_lshl_b32 s0, s2, 8
	s_and_b32 s0, s0, 0x300
	v_add_u32_e32 v12, s0, v16
	v_ashrrev_i32_e32 v13, 31, v12
	v_readlane_b32 s4, v254, 14
	v_lshlrev_b64 v[4:5], 2, v[12:13]
	v_readlane_b32 s5, v254, 15
	v_readlane_b32 s6, v254, 16
	v_readlane_b32 s7, v254, 17
	s_waitcnt vmcnt(2)
	v_lshl_add_u64 v[8:9], s[4:5], 0, v[4:5]
	s_movk_i32 s1, 0x4000
	v_lshl_add_u64 v[10:11], s[6:7], 0, v[4:5]
	v_add_co_u32_e64 v4, s[42:43], s76, v8
	s_lshl_b32 s66, s0, 1
	s_nop 0
	v_addc_co_u32_e64 v5, s[42:43], 0, v9, s[42:43]
	v_add_co_u32_e64 v6, s[42:43], s1, v8
	s_movk_i32 s1, 0x6000
	s_nop 0
	v_addc_co_u32_e64 v7, s[42:43], 0, v9, s[42:43]
	v_add_co_u32_e64 v14, s[42:43], s1, v8
	s_mov_b32 s1, 0x8000
	s_nop 0
	v_addc_co_u32_e64 v15, s[42:43], 0, v9, s[42:43]
	v_add_co_u32_e64 v56, s[42:43], s1, v8
	s_mov_b32 s1, 0xa000
	s_nop 0
	v_addc_co_u32_e64 v57, s[42:43], 0, v9, s[42:43]
	v_add_co_u32_e64 v58, s[42:43], s1, v8
	s_mov_b32 s1, 0xc000
	s_nop 0
	v_addc_co_u32_e64 v59, s[42:43], 0, v9, s[42:43]
	v_add_co_u32_e64 v60, s[42:43], s1, v8
	s_mov_b32 s1, 0xe000
	s_nop 0
	v_addc_co_u32_e64 v61, s[42:43], 0, v9, s[42:43]
	v_add_co_u32_e64 v62, s[42:43], s1, v8
	s_mov_b32 s1, 0xf000
	s_nop 0
	v_addc_co_u32_e64 v63, s[42:43], 0, v9, s[42:43]
	v_add_co_u32_e64 v64, s[42:43], s1, v8
	s_mov_b32 s3, 0
	s_nop 0
	v_addc_co_u32_e64 v65, s[42:43], 0, v9, s[42:43]
	s_waitcnt vmcnt(0)
	ds_write_b128 v92, v[0:3]
	s_waitcnt lgkmcnt(0)
	s_barrier
	global_load_dword v126, v[4:5], off offset:-4096
	global_load_dword v127, v[4:5], off
	global_load_dword v128, v[6:7], off offset:-4096
	global_load_dword v129, v[6:7], off
	global_load_dword v130, v[14:15], off offset:-4096
	global_load_dword v131, v[14:15], off
	global_load_dword v132, v[56:57], off offset:-4096
	global_load_dword v0, v[56:57], off
	global_load_dword v1, v[58:59], off offset:-4096
	global_load_dword v2, v[58:59], off
	global_load_dword v3, v[60:61], off offset:-4096
	global_load_dword v4, v[60:61], off
	global_load_dword v5, v[62:63], off offset:-4096
	global_load_dword v6, v[62:63], off
	global_load_dword v133, v[8:9], off
	global_load_dword v7, v[64:65], off
	global_load_dword v134, v[10:11], off
	v_lshrrev_b32_e32 v10, 5, v16
	v_and_b32_e32 v11, 31, v16
	v_lshlrev_b32_e32 v10, 12, v10
	v_lshl_or_b32 v10, v11, 4, v10
	v_mov_b32_e32 v11, 0
	s_lshl_b32 s1, s0, 5
	s_add_i32 s1, s1, s72
	s_lshl_b32 s1, s1, 9
	v_add_u32_e32 v10, s1, v10
	v_lshl_add_u64 v[10:11], s[52:53], 0, v[10:11]
	v_lshl_add_u64 v[8:9], v[20:21], 0, s[66:67]
	v_lshl_add_u64 v[12:13], v[12:13], 1, s[84:85]
	v_mov_b32_e32 v58, 0
.LBB0_224:
	s_lshl_b32 s0, s3, 10
	s_add_i32 s0, s0, 0x10000
	v_mov_b32_e32 v14, s0
	ds_read_b128 v[60:63], v14
	ds_read_b128 v[64:67], v14 offset:16
	ds_read_b128 v[68:71], v14 offset:32
	ds_read_b128 v[72:75], v14 offset:48
	s_lshl_b32 s20, s3, 4
	s_waitcnt vmcnt(0) lgkmcnt(3)
	v_fma_f32 v56, v133, v60, v134
	v_fmac_f32_e32 v56, v126, v61
	v_fmac_f32_e32 v56, v127, v62
	v_fmac_f32_e32 v56, v128, v63
	s_waitcnt lgkmcnt(2)
	v_fmac_f32_e32 v56, v129, v64
	v_fmac_f32_e32 v56, v130, v65
	v_fmac_f32_e32 v56, v131, v66
	v_fmac_f32_e32 v56, v132, v67
	s_waitcnt lgkmcnt(1)
	v_fmac_f32_e32 v56, v0, v68
	v_fmac_f32_e32 v56, v1, v69
	v_pk_mul_f32 v[14:15], v[2:3], v[70:71]
	s_or_b32 s50, s20, s72
	v_add_f32_e32 v14, v56, v14
	v_add_f32_e32 v56, v14, v15
	s_waitcnt lgkmcnt(0)
	v_pk_mul_f32 v[14:15], v[4:5], v[72:73]
	s_ashr_i32 s51, s50, 31
	v_add_f32_e32 v14, v56, v14
	v_add_f32_e32 v56, v14, v15
	v_pk_mul_f32 v[14:15], v[6:7], v[74:75]
	s_lshl_b64 s[0:1], s[50:51], 12
	v_add_f32_e32 v14, v56, v14
	v_add_f32_e32 v14, v14, v15
	v_min_f32_e32 v15, 0, v14
	v_mul_f32_e64 v14, |v14|, s65
	v_exp_f32_e32 v14, v14
	s_or_b32 s66, s20, 1
	s_or_b32 s74, s66, s72
	s_ashr_i32 s75, s74, 31
	v_add_f32_e32 v14, 1.0, v14
	v_cmp_gt_f32_e64 s[42:43], s80, v14
	s_or_b32 s73, s20, 2
	s_or_b32 s76, s73, s72
	v_cndmask_b32_e64 v56, 0, 32, s[42:43]
	v_ldexp_f32 v14, v14, v56
	v_log_f32_e32 v14, v14
	s_ashr_i32 s77, s76, 31
	s_or_b32 s68, s20, 3
	s_or_b32 s82, s68, s72
	v_mul_f32_e32 v56, 0x3f317217, v14
	v_fma_f32 v56, v14, s81, -v56
	v_fmac_f32_e32 v56, 0x3377d1cf, v14
	v_fmac_f32_e32 v56, 0x3f317217, v14
	v_cmp_lt_f32_e64 s[44:45], |v14|, s71
	s_ashr_i32 s83, s82, 31
	s_or_b32 s69, s20, 4
	v_cndmask_b32_e64 v14, v14, v56, s[44:45]
	v_cndmask_b32_e64 v56, 0, v236, s[42:43]
	v_sub_f32_e32 v14, v14, v56
	v_sub_f32_e32 v14, v15, v14
	v_fmac_f32_e32 v58, 0x3d800000, v14
	v_lshl_add_u64 v[14:15], v[12:13], 0, s[0:1]
	global_load_ushort v56, v[14:15], off
	s_lshl_b32 s0, s66, 6
	s_add_i32 s0, s0, 0x10000
	s_or_b32 s96, s69, s72
	s_ashr_i32 s97, s96, 31
	s_or_b32 s10, s20, 5
	s_or_b32 s8, s10, s72
	s_ashr_i32 s9, s8, 31
	s_or_b32 s11, s20, 6
	s_or_b32 s46, s11, s72
	s_ashr_i32 s47, s46, 31
	s_or_b32 s12, s20, 7
	s_or_b32 s60, s12, s72
	s_ashr_i32 s61, s60, 31
	s_or_b32 s13, s20, 8
	s_or_b32 s62, s13, s72
	s_ashr_i32 s63, s62, 31
	s_or_b32 s14, s20, 9
	s_or_b32 s56, s14, s72
	s_ashr_i32 s57, s56, 31
	s_or_b32 s15, s20, 10
	s_or_b32 s16, s20, 11
	s_or_b32 s6, s16, s72
	s_ashr_i32 s7, s6, 31
	s_or_b32 s17, s20, 12
	s_or_b32 s54, s17, s72
	s_ashr_i32 s55, s54, 31
	s_or_b32 s18, s20, 13
	s_or_b32 s48, s18, s72
	s_ashr_i32 s49, s48, 31
	s_or_b32 s19, s20, 14
	s_or_b32 s20, s20, 15
	s_lshl_b32 s21, s20, 6
	s_add_i32 s21, s21, 0x10000
	v_mul_f32_e32 v161, 0x3fb8aa3b, v58
	v_exp_f32_e32 v161, v161
	v_lshl_add_u32 v179, s73, 9, v112
	v_lshl_add_u32 v181, s68, 9, v113
	v_lshl_add_u32 v192, s12, 9, v117
	s_waitcnt vmcnt(0)
	v_lshlrev_b32_e32 v160, 16, v56
	v_mov_b32_e32 v56, s0
	ds_read_b128 v[60:63], v56
	ds_read_b128 v[64:67], v56 offset:16
	ds_read_b128 v[68:71], v56 offset:32
	ds_read_b128 v[72:75], v56 offset:48
	s_lshl_b64 s[0:1], s[74:75], 12
	s_waitcnt lgkmcnt(3)
	v_fma_f32 v59, v133, v60, v134
	v_fmac_f32_e32 v59, v126, v61
	v_fmac_f32_e32 v59, v127, v62
	v_fmac_f32_e32 v59, v128, v63
	s_waitcnt lgkmcnt(2)
	v_fmac_f32_e32 v59, v129, v64
	v_fmac_f32_e32 v59, v130, v65
	v_fmac_f32_e32 v59, v131, v66
	v_fmac_f32_e32 v59, v132, v67
	s_waitcnt lgkmcnt(1)
	v_fmac_f32_e32 v59, v0, v68
	v_fmac_f32_e32 v59, v1, v69
	v_pk_mul_f32 v[56:57], v[2:3], v[70:71]
	v_mul_f32_e32 v160, 0x3d800000, v160
	v_add_f32_e32 v56, v59, v56
	v_add_f32_e32 v59, v56, v57
	s_waitcnt lgkmcnt(0)
	v_pk_mul_f32 v[56:57], v[4:5], v[72:73]
	v_mul_f32_e32 v160, v160, v161
	v_add_f32_e32 v56, v59, v56
	v_add_f32_e32 v59, v56, v57
	v_pk_mul_f32 v[56:57], v[6:7], v[74:75]
	s_nop 0
	v_add_f32_e32 v56, v59, v56
	v_add_f32_e32 v56, v56, v57
	v_min_f32_e32 v57, 0, v56
	v_mul_f32_e64 v56, |v56|, s65
	v_exp_f32_e32 v56, v56
	s_nop 0
	v_add_f32_e32 v56, 1.0, v56
	v_cmp_gt_f32_e64 s[42:43], s80, v56
	s_nop 1
	v_cndmask_b32_e64 v59, 0, 32, s[42:43]
	v_ldexp_f32 v56, v56, v59
	v_log_f32_e32 v56, v56
	s_nop 0
	v_mul_f32_e32 v59, 0x3f317217, v56
	v_fma_f32 v59, v56, s81, -v59
	v_fmac_f32_e32 v59, 0x3377d1cf, v56
	v_fmac_f32_e32 v59, 0x3f317217, v56
	v_cmp_lt_f32_e64 s[44:45], |v56|, s71
	s_nop 1
	v_cndmask_b32_e64 v56, v56, v59, s[44:45]
	v_cndmask_b32_e64 v59, 0, v236, s[42:43]
	v_sub_f32_e32 v56, v56, v59
	v_sub_f32_e32 v56, v57, v56
	v_fmamk_f32 v59, v56, 0x3d800000, v58
	v_lshl_add_u64 v[56:57], v[12:13], 0, s[0:1]
	global_load_ushort v60, v[56:57], off
	s_lshl_b32 s0, s73, 6
	s_add_i32 s0, s0, 0x10000
	v_mov_b32_e32 v72, s0
	s_lshl_b64 s[0:1], s[76:77], 12
	v_mul_f32_e32 v58, 0xbfb8aa3b, v58
	v_exp_f32_e32 v58, v58
	s_waitcnt vmcnt(0)
	v_lshlrev_b32_e32 v88, 16, v60
	ds_read_b128 v[60:63], v72
	ds_read_b128 v[64:67], v72 offset:16
	ds_read_b128 v[68:71], v72 offset:32
	ds_read_b128 v[72:75], v72 offset:48
	s_waitcnt lgkmcnt(3)
	v_fma_f32 v76, v133, v60, v134
	v_fmac_f32_e32 v76, v126, v61
	v_fmac_f32_e32 v76, v127, v62
	v_fmac_f32_e32 v76, v128, v63
	s_waitcnt lgkmcnt(2)
	v_fmac_f32_e32 v76, v129, v64
	v_fmac_f32_e32 v76, v130, v65
	v_fmac_f32_e32 v76, v131, v66
	v_fmac_f32_e32 v76, v132, v67
	s_waitcnt lgkmcnt(1)
	v_fmac_f32_e32 v76, v0, v68
	v_fmac_f32_e32 v76, v1, v69
	v_pk_mul_f32 v[60:61], v[2:3], v[70:71]
	s_nop 0
	v_add_f32_e32 v60, v76, v60
	v_add_f32_e32 v62, v60, v61
	s_waitcnt lgkmcnt(0)
	v_pk_mul_f32 v[60:61], v[4:5], v[72:73]
	s_nop 0
	v_add_f32_e32 v60, v62, v60
	v_add_f32_e32 v62, v60, v61
	v_pk_mul_f32 v[60:61], v[6:7], v[74:75]
	s_nop 0
	v_add_f32_e32 v60, v62, v60
	v_add_f32_e32 v60, v60, v61
	v_min_f32_e32 v61, 0, v60
	v_mul_f32_e64 v60, |v60|, s65
	v_exp_f32_e32 v60, v60
	s_nop 0
	v_add_f32_e32 v60, 1.0, v60
	v_cmp_gt_f32_e64 s[42:43], s80, v60
	s_nop 1
	v_cndmask_b32_e64 v62, 0, 32, s[42:43]
	v_ldexp_f32 v60, v60, v62
	v_log_f32_e32 v60, v60
	s_nop 0
	v_mul_f32_e32 v62, 0x3f317217, v60
	v_fma_f32 v62, v60, s81, -v62
	v_fmac_f32_e32 v62, 0x3377d1cf, v60
	v_fmac_f32_e32 v62, 0x3f317217, v60
	v_cmp_lt_f32_e64 s[44:45], |v60|, s71
	s_nop 1
	v_cndmask_b32_e64 v60, v60, v62, s[44:45]
	v_cndmask_b32_e64 v62, 0, v236, s[42:43]
	v_sub_f32_e32 v60, v60, v62
	v_sub_f32_e32 v60, v61, v60
	v_fmamk_f32 v89, v60, 0x3d800000, v59
	v_lshl_add_u64 v[60:61], v[12:13], 0, s[0:1]
	global_load_ushort v62, v[60:61], off
	s_lshl_b32 s0, s68, 6
	s_add_i32 s0, s0, 0x10000
	v_mov_b32_e32 v74, s0
	s_lshl_b64 s[0:1], s[82:83], 12
	s_waitcnt vmcnt(0)
	v_lshlrev_b32_e32 v90, 16, v62
	ds_read_b128 v[62:65], v74
	ds_read_b128 v[66:69], v74 offset:16
	ds_read_b128 v[70:73], v74 offset:32
	ds_read_b128 v[74:77], v74 offset:48
	s_waitcnt lgkmcnt(3)
	v_fma_f32 v78, v133, v62, v134
	v_fmac_f32_e32 v78, v126, v63
	v_fmac_f32_e32 v78, v127, v64
	v_fmac_f32_e32 v78, v128, v65
	s_waitcnt lgkmcnt(2)
	v_fmac_f32_e32 v78, v129, v66
	v_fmac_f32_e32 v78, v130, v67
	v_fmac_f32_e32 v78, v131, v68
	v_fmac_f32_e32 v78, v132, v69
	s_waitcnt lgkmcnt(1)
	v_fmac_f32_e32 v78, v0, v70
	v_fmac_f32_e32 v78, v1, v71
	v_pk_mul_f32 v[62:63], v[2:3], v[72:73]
	s_nop 0
	v_add_f32_e32 v62, v78, v62
	v_add_f32_e32 v64, v62, v63
	s_waitcnt lgkmcnt(0)
	v_pk_mul_f32 v[62:63], v[4:5], v[74:75]
	s_nop 0
	v_add_f32_e32 v62, v64, v62
	v_add_f32_e32 v64, v62, v63
	v_pk_mul_f32 v[62:63], v[6:7], v[76:77]
	s_nop 0
	v_add_f32_e32 v62, v64, v62
	v_add_f32_e32 v62, v62, v63
	v_min_f32_e32 v63, 0, v62
	v_mul_f32_e64 v62, |v62|, s65
	v_exp_f32_e32 v62, v62
	s_nop 0
	v_add_f32_e32 v62, 1.0, v62
	v_cmp_gt_f32_e64 s[42:43], s80, v62
	s_nop 1
	v_cndmask_b32_e64 v64, 0, 32, s[42:43]
	v_ldexp_f32 v62, v62, v64
	v_log_f32_e32 v62, v62
	s_nop 0
	v_mul_f32_e32 v64, 0x3f317217, v62
	v_fma_f32 v64, v62, s81, -v64
	v_fmac_f32_e32 v64, 0x3377d1cf, v62
	v_fmac_f32_e32 v64, 0x3f317217, v62
	v_cmp_lt_f32_e64 s[44:45], |v62|, s71
	s_nop 1
	v_cndmask_b32_e64 v62, v62, v64, s[44:45]
	v_cndmask_b32_e64 v64, 0, v236, s[42:43]
	v_sub_f32_e32 v62, v62, v64
	v_sub_f32_e32 v62, v63, v62
	v_fmamk_f32 v91, v62, 0x3d800000, v89
	v_lshl_add_u64 v[62:63], v[12:13], 0, s[0:1]
	global_load_ushort v64, v[62:63], off
	s_lshl_b32 s0, s69, 6
	s_add_i32 s0, s0, 0x10000
	v_mov_b32_e32 v76, s0
	s_lshl_b64 s[0:1], s[96:97], 12
	s_waitcnt vmcnt(0)
	v_lshlrev_b32_e32 v136, 16, v64
	ds_read_b128 v[64:67], v76
	ds_read_b128 v[68:71], v76 offset:16
	ds_read_b128 v[72:75], v76 offset:32
	ds_read_b128 v[76:79], v76 offset:48
	s_waitcnt lgkmcnt(3)
	v_fma_f32 v80, v133, v64, v134
	v_fmac_f32_e32 v80, v126, v65
	v_fmac_f32_e32 v80, v127, v66
	v_fmac_f32_e32 v80, v128, v67
	s_waitcnt lgkmcnt(2)
	v_fmac_f32_e32 v80, v129, v68
	v_fmac_f32_e32 v80, v130, v69
	v_fmac_f32_e32 v80, v131, v70
	v_fmac_f32_e32 v80, v132, v71
	s_waitcnt lgkmcnt(1)
	v_fmac_f32_e32 v80, v0, v72
	v_fmac_f32_e32 v80, v1, v73
	v_pk_mul_f32 v[64:65], v[2:3], v[74:75]
	s_nop 0
	v_add_f32_e32 v64, v80, v64
	v_add_f32_e32 v66, v64, v65
	s_waitcnt lgkmcnt(0)
	v_pk_mul_f32 v[64:65], v[4:5], v[76:77]
	s_nop 0
	v_add_f32_e32 v64, v66, v64
	v_add_f32_e32 v66, v64, v65
	v_pk_mul_f32 v[64:65], v[6:7], v[78:79]
	s_nop 0
	v_add_f32_e32 v64, v66, v64
	v_add_f32_e32 v64, v64, v65
	v_min_f32_e32 v65, 0, v64
	v_mul_f32_e64 v64, |v64|, s65
	v_exp_f32_e32 v64, v64
	s_nop 0
	v_add_f32_e32 v64, 1.0, v64
	v_cmp_gt_f32_e64 s[42:43], s80, v64
	s_nop 1
	v_cndmask_b32_e64 v66, 0, 32, s[42:43]
	v_ldexp_f32 v64, v64, v66
	v_log_f32_e32 v64, v64
	s_nop 0
	v_mul_f32_e32 v66, 0x3f317217, v64
	v_fma_f32 v66, v64, s81, -v66
	v_fmac_f32_e32 v66, 0x3377d1cf, v64
	v_fmac_f32_e32 v66, 0x3f317217, v64
	v_cmp_lt_f32_e64 s[44:45], |v64|, s71
	s_nop 1
	v_cndmask_b32_e64 v64, v64, v66, s[44:45]
	v_cndmask_b32_e64 v66, 0, v236, s[42:43]
	v_sub_f32_e32 v64, v64, v66
	v_sub_f32_e32 v64, v65, v64
	v_fmamk_f32 v137, v64, 0x3d800000, v91
	v_lshl_add_u64 v[64:65], v[12:13], 0, s[0:1]
	global_load_ushort v66, v[64:65], off
	s_lshl_b32 s0, s10, 6
	s_add_i32 s0, s0, 0x10000
	v_mov_b32_e32 v78, s0
	s_lshl_b64 s[0:1], s[8:9], 12
	s_lshl_b64 s[8:9], s[8:9], 11
	s_waitcnt vmcnt(0)
	v_lshlrev_b32_e32 v138, 16, v66
	ds_read_b128 v[66:69], v78
	ds_read_b128 v[70:73], v78 offset:16
	ds_read_b128 v[74:77], v78 offset:32
	ds_read_b128 v[78:81], v78 offset:48
	s_waitcnt lgkmcnt(3)
	v_fma_f32 v82, v133, v66, v134
	v_fmac_f32_e32 v82, v126, v67
	v_fmac_f32_e32 v82, v127, v68
	v_fmac_f32_e32 v82, v128, v69
	s_waitcnt lgkmcnt(2)
	v_fmac_f32_e32 v82, v129, v70
	v_fmac_f32_e32 v82, v130, v71
	v_fmac_f32_e32 v82, v131, v72
	v_fmac_f32_e32 v82, v132, v73
	s_waitcnt lgkmcnt(1)
	v_fmac_f32_e32 v82, v0, v74
	v_fmac_f32_e32 v82, v1, v75
	v_pk_mul_f32 v[66:67], v[2:3], v[76:77]
	s_nop 0
	v_add_f32_e32 v66, v82, v66
	v_add_f32_e32 v68, v66, v67
	s_waitcnt lgkmcnt(0)
	v_pk_mul_f32 v[66:67], v[4:5], v[78:79]
	s_nop 0
	v_add_f32_e32 v66, v68, v66
	v_add_f32_e32 v68, v66, v67
	v_pk_mul_f32 v[66:67], v[6:7], v[80:81]
	s_nop 0
	v_add_f32_e32 v66, v68, v66
	v_add_f32_e32 v66, v66, v67
	v_min_f32_e32 v67, 0, v66
	v_mul_f32_e64 v66, |v66|, s65
	v_exp_f32_e32 v66, v66
	s_nop 0
	v_add_f32_e32 v66, 1.0, v66
	v_cmp_gt_f32_e64 s[42:43], s80, v66
	s_nop 1
	v_cndmask_b32_e64 v68, 0, 32, s[42:43]
	v_ldexp_f32 v66, v66, v68
	v_log_f32_e32 v66, v66
	s_nop 0
	v_mul_f32_e32 v68, 0x3f317217, v66
	v_fma_f32 v68, v66, s81, -v68
	v_fmac_f32_e32 v68, 0x3377d1cf, v66
	v_fmac_f32_e32 v68, 0x3f317217, v66
	v_cmp_lt_f32_e64 s[44:45], |v66|, s71
	s_nop 1
	v_cndmask_b32_e64 v66, v66, v68, s[44:45]
	v_cndmask_b32_e64 v68, 0, v236, s[42:43]
	v_sub_f32_e32 v66, v66, v68
	v_sub_f32_e32 v66, v67, v66
	v_fmamk_f32 v139, v66, 0x3d800000, v137
	v_lshl_add_u64 v[66:67], v[12:13], 0, s[0:1]
	global_load_ushort v68, v[66:67], off
	s_lshl_b32 s0, s11, 6
	s_add_i32 s0, s0, 0x10000
	v_mov_b32_e32 v80, s0
	s_lshl_b64 s[0:1], s[46:47], 12
	s_waitcnt vmcnt(0)
	v_lshlrev_b32_e32 v140, 16, v68
	ds_read_b128 v[68:71], v80
	ds_read_b128 v[72:75], v80 offset:16
	ds_read_b128 v[76:79], v80 offset:32
	ds_read_b128 v[80:83], v80 offset:48
	s_waitcnt lgkmcnt(3)
	v_fma_f32 v84, v133, v68, v134
	v_fmac_f32_e32 v84, v126, v69
	v_fmac_f32_e32 v84, v127, v70
	v_fmac_f32_e32 v84, v128, v71
	s_waitcnt lgkmcnt(2)
	v_fmac_f32_e32 v84, v129, v72
	v_fmac_f32_e32 v84, v130, v73
	v_fmac_f32_e32 v84, v131, v74
	v_fmac_f32_e32 v84, v132, v75
	s_waitcnt lgkmcnt(1)
	v_fmac_f32_e32 v84, v0, v76
	v_fmac_f32_e32 v84, v1, v77
	v_pk_mul_f32 v[68:69], v[2:3], v[78:79]
	s_nop 0
	v_add_f32_e32 v68, v84, v68
	v_add_f32_e32 v70, v68, v69
	s_waitcnt lgkmcnt(0)
	v_pk_mul_f32 v[68:69], v[4:5], v[80:81]
	s_nop 0
	v_add_f32_e32 v68, v70, v68
	v_add_f32_e32 v70, v68, v69
	v_pk_mul_f32 v[68:69], v[6:7], v[82:83]
	s_nop 0
	v_add_f32_e32 v68, v70, v68
	v_add_f32_e32 v68, v68, v69
	v_min_f32_e32 v69, 0, v68
	v_mul_f32_e64 v68, |v68|, s65
	v_exp_f32_e32 v68, v68
	s_nop 0
	v_add_f32_e32 v68, 1.0, v68
	v_cmp_gt_f32_e64 s[42:43], s80, v68
	s_nop 1
	v_cndmask_b32_e64 v70, 0, 32, s[42:43]
	v_ldexp_f32 v68, v68, v70
	v_log_f32_e32 v68, v68
	s_nop 0
	v_mul_f32_e32 v70, 0x3f317217, v68
	v_fma_f32 v70, v68, s81, -v70
	v_fmac_f32_e32 v70, 0x3377d1cf, v68
	v_fmac_f32_e32 v70, 0x3f317217, v68
	v_cmp_lt_f32_e64 s[44:45], |v68|, s71
	s_nop 1
	v_cndmask_b32_e64 v68, v68, v70, s[44:45]
	v_cndmask_b32_e64 v70, 0, v236, s[42:43]
	v_sub_f32_e32 v68, v68, v70
	v_sub_f32_e32 v68, v69, v68
	v_fmamk_f32 v141, v68, 0x3d800000, v139
	v_lshl_add_u64 v[68:69], v[12:13], 0, s[0:1]
	global_load_ushort v70, v[68:69], off
	s_lshl_b32 s0, s12, 6
	s_add_i32 s0, s0, 0x10000
	v_mov_b32_e32 v82, s0
	s_lshl_b64 s[0:1], s[60:61], 12
	s_waitcnt vmcnt(0)
	v_lshlrev_b32_e32 v142, 16, v70
	ds_read_b128 v[70:73], v82
	ds_read_b128 v[74:77], v82 offset:16
	ds_read_b128 v[78:81], v82 offset:32
	ds_read_b128 v[82:85], v82 offset:48
	s_waitcnt lgkmcnt(3)
	v_fma_f32 v86, v133, v70, v134
	v_fmac_f32_e32 v86, v126, v71
	v_fmac_f32_e32 v86, v127, v72
	v_fmac_f32_e32 v86, v128, v73
	s_waitcnt lgkmcnt(2)
	v_fmac_f32_e32 v86, v129, v74
	v_fmac_f32_e32 v86, v130, v75
	v_fmac_f32_e32 v86, v131, v76
	v_fmac_f32_e32 v86, v132, v77
	s_waitcnt lgkmcnt(1)
	v_fmac_f32_e32 v86, v0, v78
	v_fmac_f32_e32 v86, v1, v79
	v_pk_mul_f32 v[70:71], v[2:3], v[80:81]
	s_nop 0
	v_add_f32_e32 v70, v86, v70
	v_add_f32_e32 v72, v70, v71
	s_waitcnt lgkmcnt(0)
	v_pk_mul_f32 v[70:71], v[4:5], v[82:83]
	s_nop 0
	v_add_f32_e32 v70, v72, v70
	v_add_f32_e32 v72, v70, v71
	v_pk_mul_f32 v[70:71], v[6:7], v[84:85]
	s_nop 0
	v_add_f32_e32 v70, v72, v70
	v_add_f32_e32 v70, v70, v71
	v_min_f32_e32 v71, 0, v70
	v_mul_f32_e64 v70, |v70|, s65
	v_exp_f32_e32 v70, v70
	s_nop 0
	v_add_f32_e32 v70, 1.0, v70
	v_cmp_gt_f32_e64 s[42:43], s80, v70
	s_nop 1
	v_cndmask_b32_e64 v72, 0, 32, s[42:43]
	v_ldexp_f32 v70, v70, v72
	v_log_f32_e32 v70, v70
	s_nop 0
	v_mul_f32_e32 v72, 0x3f317217, v70
	v_fma_f32 v72, v70, s81, -v72
	v_fmac_f32_e32 v72, 0x3377d1cf, v70
	v_fmac_f32_e32 v72, 0x3f317217, v70
	v_cmp_lt_f32_e64 s[44:45], |v70|, s71
	s_nop 1
	v_cndmask_b32_e64 v70, v70, v72, s[44:45]
	v_cndmask_b32_e64 v72, 0, v236, s[42:43]
	v_sub_f32_e32 v70, v70, v72
	v_sub_f32_e32 v70, v71, v70
	v_fmamk_f32 v143, v70, 0x3d800000, v141
	v_lshl_add_u64 v[70:71], v[12:13], 0, s[0:1]
	global_load_ushort v72, v[70:71], off
	s_lshl_b32 s0, s13, 6
	s_add_i32 s0, s0, 0x10000
	v_mov_b32_e32 v84, s0
	s_lshl_b64 s[0:1], s[62:63], 12
	s_waitcnt vmcnt(0)
	v_lshlrev_b32_e32 v144, 16, v72
	ds_read_b128 v[72:75], v84
	ds_read_b128 v[76:79], v84 offset:16
	ds_read_b128 v[80:83], v84 offset:32
	ds_read_b128 v[84:87], v84 offset:48
	s_waitcnt lgkmcnt(3)
	v_fma_f32 v135, v133, v72, v134
	v_fmac_f32_e32 v135, v126, v73
	v_fmac_f32_e32 v135, v127, v74
	v_fmac_f32_e32 v135, v128, v75
	s_waitcnt lgkmcnt(2)
	v_fmac_f32_e32 v135, v129, v76
	v_fmac_f32_e32 v135, v130, v77
	v_fmac_f32_e32 v135, v131, v78
	v_fmac_f32_e32 v135, v132, v79
	s_waitcnt lgkmcnt(1)
	v_fmac_f32_e32 v135, v0, v80
	v_fmac_f32_e32 v135, v1, v81
	v_pk_mul_f32 v[72:73], v[2:3], v[82:83]
	s_nop 0
	v_add_f32_e32 v72, v135, v72
	v_add_f32_e32 v74, v72, v73
	s_waitcnt lgkmcnt(0)
	v_pk_mul_f32 v[72:73], v[4:5], v[84:85]
	s_nop 0
	v_add_f32_e32 v72, v74, v72
	v_add_f32_e32 v74, v72, v73
	v_pk_mul_f32 v[72:73], v[6:7], v[86:87]
	s_nop 0
	v_add_f32_e32 v72, v74, v72
	v_add_f32_e32 v72, v72, v73
	v_min_f32_e32 v73, 0, v72
	v_mul_f32_e64 v72, |v72|, s65
	v_exp_f32_e32 v72, v72
	s_nop 0
	v_add_f32_e32 v72, 1.0, v72
	v_cmp_gt_f32_e64 s[42:43], s80, v72
	s_nop 1
	v_cndmask_b32_e64 v74, 0, 32, s[42:43]
	v_ldexp_f32 v72, v72, v74
	v_log_f32_e32 v72, v72
	s_nop 0
	v_mul_f32_e32 v74, 0x3f317217, v72
	v_fma_f32 v74, v72, s81, -v74
	v_fmac_f32_e32 v74, 0x3377d1cf, v72
	v_fmac_f32_e32 v74, 0x3f317217, v72
	v_cmp_lt_f32_e64 s[44:45], |v72|, s71
	s_nop 1
	v_cndmask_b32_e64 v72, v72, v74, s[44:45]
	v_cndmask_b32_e64 v74, 0, v236, s[42:43]
	v_sub_f32_e32 v72, v72, v74
	v_sub_f32_e32 v72, v73, v72
	v_fmamk_f32 v145, v72, 0x3d800000, v143
	v_lshl_add_u64 v[72:73], v[12:13], 0, s[0:1]
	global_load_ushort v74, v[72:73], off
	s_lshl_b32 s0, s14, 6
	s_add_i32 s0, s0, 0x10000
	v_mov_b32_e32 v86, s0
	s_lshl_b64 s[0:1], s[56:57], 12
	s_waitcnt vmcnt(0)
	v_lshlrev_b32_e32 v146, 16, v74
	ds_read_b128 v[74:77], v86
	ds_read_b128 v[78:81], v86 offset:16
	ds_read_b128 v[82:85], v86 offset:32
	ds_read_b128 v[148:151], v86 offset:48
	s_waitcnt lgkmcnt(3)
	v_fma_f32 v86, v133, v74, v134
	v_fmac_f32_e32 v86, v126, v75
	v_fmac_f32_e32 v86, v127, v76
	v_fmac_f32_e32 v86, v128, v77
	s_waitcnt lgkmcnt(2)
	v_fmac_f32_e32 v86, v129, v78
	v_fmac_f32_e32 v86, v130, v79
	v_fmac_f32_e32 v86, v131, v80
	v_fmac_f32_e32 v86, v132, v81
	s_waitcnt lgkmcnt(1)
	v_fmac_f32_e32 v86, v0, v82
	v_fmac_f32_e32 v86, v1, v83
	v_pk_mul_f32 v[74:75], v[2:3], v[84:85]
	s_nop 0
	v_add_f32_e32 v74, v86, v74
	v_add_f32_e32 v76, v74, v75
	s_waitcnt lgkmcnt(0)
	v_pk_mul_f32 v[74:75], v[4:5], v[148:149]
	s_nop 0
	v_add_f32_e32 v74, v76, v74
	v_add_f32_e32 v76, v74, v75
	v_pk_mul_f32 v[74:75], v[6:7], v[150:151]
	s_nop 0
	v_add_f32_e32 v74, v76, v74
	v_add_f32_e32 v74, v74, v75
	v_min_f32_e32 v75, 0, v74
	v_mul_f32_e64 v74, |v74|, s65
	v_exp_f32_e32 v74, v74
	s_nop 0
	v_add_f32_e32 v74, 1.0, v74
	v_cmp_gt_f32_e64 s[42:43], s80, v74
	s_nop 1
	v_cndmask_b32_e64 v76, 0, 32, s[42:43]
	v_ldexp_f32 v74, v74, v76
	v_log_f32_e32 v74, v74
	s_nop 0
	v_mul_f32_e32 v76, 0x3f317217, v74
	v_fma_f32 v76, v74, s81, -v76
	v_fmac_f32_e32 v76, 0x3377d1cf, v74
	v_fmac_f32_e32 v76, 0x3f317217, v74
	v_cmp_lt_f32_e64 s[44:45], |v74|, s71
	s_nop 1
	v_cndmask_b32_e64 v74, v74, v76, s[44:45]
	v_cndmask_b32_e64 v76, 0, v236, s[42:43]
	v_sub_f32_e32 v74, v74, v76
	v_sub_f32_e32 v74, v75, v74
	v_fmamk_f32 v147, v74, 0x3d800000, v145
	v_lshl_add_u64 v[74:75], v[12:13], 0, s[0:1]
	global_load_ushort v76, v[74:75], off
	s_lshl_b32 s0, s15, 6
	s_add_i32 s0, s0, 0x10000
	v_mov_b32_e32 v135, s0
	s_or_b32 s0, s15, s72
	s_ashr_i32 s1, s0, 31
	s_lshl_b64 s[4:5], s[0:1], 12
	v_cvt_pk_bf16_f32 v160, v160, s0
	s_waitcnt vmcnt(0)
	v_lshlrev_b32_e32 v148, 16, v76
	ds_read_b128 v[76:79], v135
	ds_read_b128 v[80:83], v135 offset:16
	ds_read_b128 v[84:87], v135 offset:32
	ds_read_b128 v[150:153], v135 offset:48
	s_waitcnt lgkmcnt(3)
	v_fma_f32 v135, v133, v76, v134
	v_fmac_f32_e32 v135, v126, v77
	v_fmac_f32_e32 v135, v127, v78
	v_fmac_f32_e32 v135, v128, v79
	s_waitcnt lgkmcnt(2)
	v_fmac_f32_e32 v135, v129, v80
	v_fmac_f32_e32 v135, v130, v81
	v_fmac_f32_e32 v135, v131, v82
	v_fmac_f32_e32 v135, v132, v83
	s_waitcnt lgkmcnt(1)
	v_fmac_f32_e32 v135, v0, v84
	v_fmac_f32_e32 v135, v1, v85
	v_pk_mul_f32 v[76:77], v[2:3], v[86:87]
	s_nop 0
	v_add_f32_e32 v76, v135, v76
	v_add_f32_e32 v78, v76, v77
	s_waitcnt lgkmcnt(0)
	v_pk_mul_f32 v[76:77], v[4:5], v[150:151]
	s_nop 0
	v_add_f32_e32 v76, v78, v76
	v_add_f32_e32 v78, v76, v77
	v_pk_mul_f32 v[76:77], v[6:7], v[152:153]
	s_nop 0
	v_add_f32_e32 v76, v78, v76
	v_add_f32_e32 v76, v76, v77
	v_min_f32_e32 v77, 0, v76
	v_mul_f32_e64 v76, |v76|, s65
	v_exp_f32_e32 v76, v76
	s_nop 0
	v_add_f32_e32 v76, 1.0, v76
	v_cmp_gt_f32_e64 s[42:43], s80, v76
	s_nop 1
	v_cndmask_b32_e64 v78, 0, 32, s[42:43]
	v_ldexp_f32 v76, v76, v78
	v_log_f32_e32 v76, v76
	s_nop 0
	v_mul_f32_e32 v78, 0x3f317217, v76
	v_fma_f32 v78, v76, s81, -v78
	v_fmac_f32_e32 v78, 0x3377d1cf, v76
	v_fmac_f32_e32 v78, 0x3f317217, v76
	v_cmp_lt_f32_e64 s[44:45], |v76|, s71
	s_nop 1
	v_cndmask_b32_e64 v76, v76, v78, s[44:45]
	v_cndmask_b32_e64 v78, 0, v236, s[42:43]
	v_sub_f32_e32 v76, v76, v78
	v_sub_f32_e32 v76, v77, v76
	v_fmamk_f32 v149, v76, 0x3d800000, v147
	v_lshl_add_u64 v[76:77], v[12:13], 0, s[4:5]
	global_load_ushort v78, v[76:77], off
	s_lshl_b32 s4, s16, 6
	s_add_i32 s4, s4, 0x10000
	v_mov_b32_e32 v86, s4
	s_lshl_b64 s[4:5], s[6:7], 12
	s_waitcnt vmcnt(0)
	v_lshlrev_b32_e32 v150, 16, v78
	ds_read_b128 v[78:81], v86
	ds_read_b128 v[82:85], v86 offset:16
	ds_read_b128 v[152:155], v86 offset:32
	ds_read_b128 v[156:159], v86 offset:48
	s_waitcnt lgkmcnt(3)
	v_fma_f32 v86, v133, v78, v134
	v_fmac_f32_e32 v86, v126, v79
	v_fmac_f32_e32 v86, v127, v80
	v_fmac_f32_e32 v86, v128, v81
	s_waitcnt lgkmcnt(2)
	v_fmac_f32_e32 v86, v129, v82
	v_fmac_f32_e32 v86, v130, v83
	v_fmac_f32_e32 v86, v131, v84
	v_fmac_f32_e32 v86, v132, v85
	s_waitcnt lgkmcnt(1)
	v_fmac_f32_e32 v86, v0, v152
	v_fmac_f32_e32 v86, v1, v153
	v_pk_mul_f32 v[78:79], v[2:3], v[154:155]
	s_nop 0
	v_add_f32_e32 v78, v86, v78
	v_add_f32_e32 v80, v78, v79
	s_waitcnt lgkmcnt(0)
	v_pk_mul_f32 v[78:79], v[4:5], v[156:157]
	s_nop 0
	v_add_f32_e32 v78, v80, v78
	v_add_f32_e32 v80, v78, v79
	v_pk_mul_f32 v[78:79], v[6:7], v[158:159]
	s_nop 0
	v_add_f32_e32 v78, v80, v78
	v_add_f32_e32 v78, v78, v79
	v_min_f32_e32 v79, 0, v78
	v_mul_f32_e64 v78, |v78|, s65
	v_exp_f32_e32 v78, v78
	s_nop 0
	v_add_f32_e32 v78, 1.0, v78
	v_cmp_gt_f32_e64 s[42:43], s80, v78
	s_nop 1
	v_cndmask_b32_e64 v80, 0, 32, s[42:43]
	v_ldexp_f32 v78, v78, v80
	v_log_f32_e32 v78, v78
	s_nop 0
	v_mul_f32_e32 v80, 0x3f317217, v78
	v_fma_f32 v80, v78, s81, -v80
	v_fmac_f32_e32 v80, 0x3377d1cf, v78
	v_fmac_f32_e32 v80, 0x3f317217, v78
	v_cmp_lt_f32_e64 s[44:45], |v78|, s71
	s_nop 1
	v_cndmask_b32_e64 v78, v78, v80, s[44:45]
	v_cndmask_b32_e64 v80, 0, v236, s[42:43]
	v_sub_f32_e32 v78, v78, v80
	v_sub_f32_e32 v78, v79, v78
	v_fmamk_f32 v151, v78, 0x3d800000, v149
	v_lshl_add_u64 v[78:79], v[12:13], 0, s[4:5]
	global_load_ushort v80, v[78:79], off
	s_lshl_b32 s4, s17, 6
	s_add_i32 s4, s4, 0x10000
	v_mov_b32_e32 v135, s4
	s_lshl_b64 s[4:5], s[54:55], 12
	s_waitcnt vmcnt(0)
	v_lshlrev_b32_e32 v152, 16, v80
	ds_read_b128 v[80:83], v135
	ds_read_b128 v[84:87], v135 offset:16
	ds_read_b128 v[154:157], v135 offset:32
	ds_read_b128 v[162:165], v135 offset:48
	s_waitcnt lgkmcnt(3)
	v_fma_f32 v135, v133, v80, v134
	v_fmac_f32_e32 v135, v126, v81
	v_fmac_f32_e32 v135, v127, v82
	v_fmac_f32_e32 v135, v128, v83
	s_waitcnt lgkmcnt(2)
	v_fmac_f32_e32 v135, v129, v84
	v_fmac_f32_e32 v135, v130, v85
	v_fmac_f32_e32 v135, v131, v86
	v_fmac_f32_e32 v135, v132, v87
	s_waitcnt lgkmcnt(1)
	v_fmac_f32_e32 v135, v0, v154
	v_fmac_f32_e32 v135, v1, v155
	v_pk_mul_f32 v[80:81], v[2:3], v[156:157]
	s_nop 0
	v_add_f32_e32 v80, v135, v80
	v_add_f32_e32 v82, v80, v81
	s_waitcnt lgkmcnt(0)
	v_pk_mul_f32 v[80:81], v[4:5], v[162:163]
	s_nop 0
	v_add_f32_e32 v80, v82, v80
	v_add_f32_e32 v82, v80, v81
	v_pk_mul_f32 v[80:81], v[6:7], v[164:165]
	s_nop 0
	v_add_f32_e32 v80, v82, v80
	v_add_f32_e32 v80, v80, v81
	v_min_f32_e32 v81, 0, v80
	v_mul_f32_e64 v80, |v80|, s65
	v_exp_f32_e32 v80, v80
	s_nop 0
	v_add_f32_e32 v80, 1.0, v80
	v_cmp_gt_f32_e64 s[42:43], s80, v80
	s_nop 1
	v_cndmask_b32_e64 v82, 0, 32, s[42:43]
	v_ldexp_f32 v80, v80, v82
	v_log_f32_e32 v80, v80
	s_nop 0
	v_mul_f32_e32 v82, 0x3f317217, v80
	v_fma_f32 v82, v80, s81, -v82
	v_fmac_f32_e32 v82, 0x3377d1cf, v80
	v_fmac_f32_e32 v82, 0x3f317217, v80
	v_cmp_lt_f32_e64 s[44:45], |v80|, s71
	s_nop 1
	v_cndmask_b32_e64 v80, v80, v82, s[44:45]
	v_cndmask_b32_e64 v82, 0, v236, s[42:43]
	v_sub_f32_e32 v80, v80, v82
	v_sub_f32_e32 v80, v81, v80
	v_fmamk_f32 v153, v80, 0x3d800000, v151
	v_lshl_add_u64 v[80:81], v[12:13], 0, s[4:5]
	global_load_ushort v82, v[80:81], off
	s_lshl_b32 s4, s18, 6
	s_add_i32 s4, s4, 0x10000
	v_mov_b32_e32 v86, s4
	s_lshl_b64 s[4:5], s[48:49], 12
	s_waitcnt vmcnt(0)
	v_lshlrev_b32_e32 v154, 16, v82
	ds_read_b128 v[82:85], v86
	ds_read_b128 v[156:159], v86 offset:16
	ds_read_b128 v[162:165], v86 offset:32
	ds_read_b128 v[166:169], v86 offset:48
	s_waitcnt lgkmcnt(3)
	v_fma_f32 v86, v133, v82, v134
	v_fmac_f32_e32 v86, v126, v83
	v_fmac_f32_e32 v86, v127, v84
	v_fmac_f32_e32 v86, v128, v85
	s_waitcnt lgkmcnt(2)
	v_fmac_f32_e32 v86, v129, v156
	v_fmac_f32_e32 v86, v130, v157
	v_fmac_f32_e32 v86, v131, v158
	v_fmac_f32_e32 v86, v132, v159
	s_waitcnt lgkmcnt(1)
	v_fmac_f32_e32 v86, v0, v162
	v_fmac_f32_e32 v86, v1, v163
	v_pk_mul_f32 v[82:83], v[2:3], v[164:165]
	s_nop 0
	v_add_f32_e32 v82, v86, v82
	v_add_f32_e32 v84, v82, v83
	s_waitcnt lgkmcnt(0)
	v_pk_mul_f32 v[82:83], v[4:5], v[166:167]
	s_nop 0
	v_add_f32_e32 v82, v84, v82
	v_add_f32_e32 v84, v82, v83
	v_pk_mul_f32 v[82:83], v[6:7], v[168:169]
	s_nop 0
	v_add_f32_e32 v82, v84, v82
	v_add_f32_e32 v82, v82, v83
	v_min_f32_e32 v83, 0, v82
	v_mul_f32_e64 v82, |v82|, s65
	v_exp_f32_e32 v82, v82
	s_nop 0
	v_add_f32_e32 v82, 1.0, v82
	v_cmp_gt_f32_e64 s[42:43], s80, v82
	s_nop 1
	v_cndmask_b32_e64 v84, 0, 32, s[42:43]
	v_ldexp_f32 v82, v82, v84
	v_log_f32_e32 v82, v82
	s_nop 0
	v_mul_f32_e32 v84, 0x3f317217, v82
	v_fma_f32 v84, v82, s81, -v84
	v_fmac_f32_e32 v84, 0x3377d1cf, v82
	v_fmac_f32_e32 v84, 0x3f317217, v82
	v_cmp_lt_f32_e64 s[44:45], |v82|, s71
	s_nop 1
	v_cndmask_b32_e64 v82, v82, v84, s[44:45]
	v_cndmask_b32_e64 v84, 0, v236, s[42:43]
	v_sub_f32_e32 v82, v82, v84
	v_sub_f32_e32 v82, v83, v82
	v_fmamk_f32 v155, v82, 0x3d800000, v153
	v_lshl_add_u64 v[82:83], v[12:13], 0, s[4:5]
	global_load_ushort v84, v[82:83], off
	s_lshl_b32 s4, s19, 6
	s_add_i32 s4, s4, 0x10000
	v_mov_b32_e32 v135, s4
	s_or_b32 s4, s19, s72
	s_ashr_i32 s5, s4, 31
	s_waitcnt vmcnt(0)
	v_lshlrev_b32_e32 v156, 16, v84
	ds_read_b128 v[84:87], v135
	ds_read_b128 v[162:165], v135 offset:16
	ds_read_b128 v[166:169], v135 offset:32
	ds_read_b128 v[170:173], v135 offset:48
	s_waitcnt lgkmcnt(3)
	v_fma_f32 v135, v133, v84, v134
	v_fmac_f32_e32 v135, v126, v85
	v_fmac_f32_e32 v135, v127, v86
	v_fmac_f32_e32 v135, v128, v87
	s_waitcnt lgkmcnt(2)
	v_fmac_f32_e32 v135, v129, v162
	v_fmac_f32_e32 v135, v130, v163
	v_fmac_f32_e32 v135, v131, v164
	v_fmac_f32_e32 v135, v132, v165
	s_waitcnt lgkmcnt(1)
	v_pk_mul_f32 v[84:85], v[0:1], v[166:167]
	s_nop 0
	v_add_f32_e32 v84, v135, v84
	v_add_f32_e32 v86, v84, v85
	v_pk_mul_f32 v[84:85], v[2:3], v[168:169]
	s_nop 0
	v_add_f32_e32 v84, v86, v84
	v_add_f32_e32 v86, v84, v85
	s_waitcnt lgkmcnt(0)
	v_pk_mul_f32 v[84:85], v[4:5], v[170:171]
	s_nop 0
	v_add_f32_e32 v84, v86, v84
	v_add_f32_e32 v86, v84, v85
	v_pk_mul_f32 v[84:85], v[6:7], v[172:173]
	s_nop 0
	v_add_f32_e32 v84, v86, v84
	v_add_f32_e32 v84, v84, v85
	v_min_f32_e32 v85, 0, v84
	v_mul_f32_e64 v84, |v84|, s65
	v_exp_f32_e32 v84, v84
	s_nop 0
	v_add_f32_e32 v84, 1.0, v84
	v_cmp_gt_f32_e64 s[42:43], s80, v84
	s_nop 1
	v_cndmask_b32_e64 v86, 0, 32, s[42:43]
	v_ldexp_f32 v84, v84, v86
	v_log_f32_e32 v84, v84
	s_nop 0
	v_mul_f32_e32 v86, 0x3f317217, v84
	v_fma_f32 v86, v84, s81, -v86
	v_fmac_f32_e32 v86, 0x3377d1cf, v84
	v_fmac_f32_e32 v86, 0x3f317217, v84
	v_cmp_lt_f32_e64 s[44:45], |v84|, s71
	s_nop 1
	v_cndmask_b32_e64 v84, v84, v86, s[44:45]
	v_cndmask_b32_e64 v86, 0, v236, s[42:43]
	v_sub_f32_e32 v84, v84, v86
	v_sub_f32_e32 v84, v85, v84
	s_lshl_b64 s[42:43], s[4:5], 12
	v_fmamk_f32 v157, v84, 0x3d800000, v155
	v_lshl_add_u64 v[84:85], v[12:13], 0, s[42:43]
	global_load_ushort v86, v[84:85], off
	s_waitcnt vmcnt(0)
	v_lshlrev_b32_e32 v158, 16, v86
	v_mov_b32_e32 v86, s21
	ds_read_b128 v[162:165], v86
	ds_read_b128 v[166:169], v86 offset:16
	ds_read_b128 v[170:173], v86 offset:32
	ds_read_b128 v[174:177], v86 offset:48
	s_waitcnt lgkmcnt(3)
	v_fma_f32 v135, v133, v162, v134
	v_fmac_f32_e32 v135, v126, v163
	v_fmac_f32_e32 v135, v127, v164
	v_fmac_f32_e32 v135, v128, v165
	s_waitcnt lgkmcnt(2)
	v_fmac_f32_e32 v135, v129, v166
	v_fmac_f32_e32 v135, v130, v167
	v_fmac_f32_e32 v135, v131, v168
	v_fmac_f32_e32 v135, v132, v169
	s_waitcnt lgkmcnt(1)
	v_pk_mul_f32 v[86:87], v[0:1], v[170:171]
	s_nop 0
	v_add_f32_e32 v86, v135, v86
	v_add_f32_e32 v135, v86, v87
	v_pk_mul_f32 v[86:87], v[2:3], v[172:173]
	v_lshl_add_u32 v173, s3, 13, v93
	v_add_f32_e32 v86, v135, v86
	v_add_f32_e32 v135, v86, v87
	s_waitcnt lgkmcnt(0)
	v_pk_mul_f32 v[86:87], v[4:5], v[174:175]
	s_nop 0
	v_add_f32_e32 v86, v135, v86
	v_add_f32_e32 v135, v86, v87
	v_pk_mul_f32 v[86:87], v[6:7], v[176:177]
	s_nop 0
	v_add_f32_e32 v86, v135, v86
	v_add_f32_e32 v86, v86, v87
	v_min_f32_e32 v87, 0, v86
	v_mul_f32_e64 v86, |v86|, s65
	v_exp_f32_e32 v86, v86
	s_nop 0
	v_add_f32_e32 v86, 1.0, v86
	v_cmp_gt_f32_e64 s[42:43], s80, v86
	s_nop 1
	v_cndmask_b32_e64 v135, 0, 32, s[42:43]
	v_ldexp_f32 v86, v86, v135
	v_log_f32_e32 v86, v86
	s_nop 0
	v_mul_f32_e32 v135, 0x3f317217, v86
	v_fma_f32 v135, v86, s81, -v135
	v_fmac_f32_e32 v135, 0x3377d1cf, v86
	v_fmac_f32_e32 v135, 0x3f317217, v86
	v_cmp_lt_f32_e64 s[44:45], |v86|, s71
	s_nop 1
	v_cndmask_b32_e64 v86, v86, v135, s[44:45]
	v_cndmask_b32_e64 v135, 0, v236, s[42:43]
	s_or_b32 s42, s20, s72
	v_sub_f32_e32 v86, v86, v135
	s_ashr_i32 s43, s42, 31
	v_sub_f32_e32 v86, v87, v86
	s_lshl_b64 s[44:45], s[42:43], 12
	v_fmamk_f32 v135, v86, 0x3d800000, v157
	v_lshl_add_u64 v[86:87], v[12:13], 0, s[44:45]
	global_load_ushort v159, v[86:87], off
	global_load_ushort v174, v[60:61], off offset:2048
	global_load_ushort v176, v[14:15], off offset:2048
	global_load_ushort v175, v[56:57], off offset:2048
	global_load_ushort v177, v[62:63], off offset:2048
	global_load_ushort v169, v[64:65], off offset:2048
	global_load_ushort v171, v[68:69], off offset:2048
	global_load_ushort v170, v[66:67], off offset:2048
	global_load_ushort v172, v[70:71], off offset:2048
	global_load_ushort v165, v[72:73], off offset:2048
	global_load_ushort v167, v[76:77], off offset:2048
	global_load_ushort v166, v[74:75], off offset:2048
	global_load_ushort v168, v[78:79], off offset:2048
	global_load_ushort v161, v[80:81], off offset:2048
	global_load_ushort v163, v[84:85], off offset:2048
	global_load_ushort v162, v[82:83], off offset:2048
	global_load_ushort v164, v[86:87], off offset:2048
	s_lshl_b64 s[44:45], s[50:51], 11
	v_lshl_add_u64 v[14:15], v[8:9], 0, s[44:45]
	global_store_short v[14:15], v160, off
	v_mul_f32_e32 v15, 0x3fb8aa3b, v59
	v_exp_f32_e32 v15, v15
	v_mul_f32_e32 v14, 0x3d800000, v88
	s_lshl_b64 s[44:45], s[74:75], 11
	v_lshl_add_u64 v[56:57], v[8:9], 0, s[44:45]
	v_mul_f32_e32 v15, v14, v15
	v_cvt_pk_bf16_f32 v178, v15, s0
	global_store_short v[56:57], v178, off
	v_mul_f32_e32 v56, 0x3fb8aa3b, v89
	v_exp_f32_e32 v56, v56
	v_mul_f32_e32 v15, 0x3d800000, v90
	s_lshl_b64 s[44:45], s[76:77], 11
	v_mul_f32_e32 v14, 0xbfb8aa3b, v59
	v_mul_f32_e32 v15, v15, v56
	v_mul_f32_e32 v56, 0xbfb8aa3b, v89
	v_exp_f32_e32 v59, v56
	v_cvt_pk_bf16_f32 v180, v15, s0
	v_lshl_add_u64 v[56:57], v[8:9], 0, s[44:45]
	global_store_short v[56:57], v180, off
	v_mul_f32_e32 v56, 0x3fb8aa3b, v91
	v_exp_f32_e32 v56, v56
	v_mul_f32_e32 v15, 0x3d800000, v136
	s_lshl_b64 s[44:45], s[82:83], 11
	v_mul_f32_e32 v62, 0x3fb8aa3b, v143
	v_mul_f32_e32 v56, v15, v56
	v_cvt_pk_bf16_f32 v182, v56, s0
	v_lshl_add_u64 v[56:57], v[8:9], 0, s[44:45]
	global_store_short v[56:57], v182, off
	v_mul_f32_e32 v57, 0x3fb8aa3b, v137
	v_exp_f32_e32 v57, v57
	v_mul_f32_e32 v56, 0x3d800000, v138
	s_lshl_b64 s[44:45], s[96:97], 11
	v_lshl_add_u64 v[60:61], v[8:9], 0, s[44:45]
	v_mul_f32_e32 v57, v56, v57
	v_cvt_pk_bf16_f32 v183, v57, s0
	global_store_short v[60:61], v183, off
	v_mul_f32_e32 v60, 0x3fb8aa3b, v139
	v_exp_f32_e32 v60, v60
	v_mul_f32_e32 v61, 0x3fb8aa3b, v141
	v_exp_f32_e32 v61, v61
	v_mul_f32_e32 v57, 0x3d800000, v140
	v_mul_f32_e32 v57, v57, v60
	v_exp_f32_e32 v62, v62
	v_cvt_pk_bf16_f32 v138, v57, s0
	v_mul_f32_e32 v57, 0x3d800000, v142
	v_mul_f32_e32 v63, 0x3fb8aa3b, v145
	v_mul_f32_e32 v61, v57, v61
	v_exp_f32_e32 v63, v63
	v_mul_f32_e32 v57, 0xbfb8aa3b, v141
	v_cvt_pk_bf16_f32 v141, v61, s0
	v_mul_f32_e32 v61, 0x3d800000, v144
	v_mul_f32_e32 v64, 0x3fb8aa3b, v147
	v_mul_f32_e32 v15, 0xbfb8aa3b, v91
	v_mul_f32_e32 v62, v61, v62
	v_exp_f32_e32 v64, v64
	v_exp_f32_e32 v14, v14
	v_exp_f32_e32 v15, v15
	v_cvt_pk_bf16_f32 v186, v62, s0
	v_mul_f32_e32 v62, 0x3d800000, v146
	v_mul_f32_e32 v65, 0x3fb8aa3b, v149
	v_mul_f32_e32 v63, v62, v63
	v_exp_f32_e32 v65, v65
	v_cvt_pk_bf16_f32 v193, v63, s0
	v_mul_f32_e32 v63, 0x3d800000, v148
	v_mul_f32_e32 v68, 0x3fb8aa3b, v151
	v_mul_f32_e32 v63, v63, v64
	v_exp_f32_e32 v68, v68
	s_waitcnt vmcnt(19)
	v_lshlrev_b32_e32 v194, 16, v176
	v_lshlrev_b32_e32 v195, 16, v174
	s_waitcnt vmcnt(17)
	v_lshlrev_b32_e32 v177, 16, v177
	v_lshlrev_b32_e32 v176, 16, v175
	v_mul_f32_e32 v56, 0xbfb8aa3b, v137
	v_mul_f32_e32 v61, 0xbfb8aa3b, v143
	v_cvt_pk_bf16_f32 v143, v63, s0
	v_mul_f32_e32 v63, 0x3d800000, v150
	v_mul_f32_e32 v69, 0x3fb8aa3b, v153
	v_pk_mul_f32 v[58:59], v[58:59], v[194:195]
	v_pk_mul_f32 v[14:15], v[14:15], v[176:177]
	v_exp_f32_e32 v56, v56
	v_mul_f32_e32 v60, 0xbfb8aa3b, v139
	v_exp_f32_e32 v57, v57
	v_mul_f32_e32 v65, v63, v65
	v_exp_f32_e32 v69, v69
	v_cvt_pk_bf16_f32 v58, v58, v59
	v_cvt_pk_bf16_f32 v14, v14, v15
	ds_write_b16 v173, v160
	v_lshl_add_u32 v160, s66, 9, v111
	v_exp_f32_e32 v60, v60
	v_lshl_add_u64 v[66:67], v[8:9], 0, s[8:9]
	s_lshl_b64 s[8:9], s[46:47], 11
	v_exp_f32_e32 v61, v61
	v_cvt_pk_bf16_f32 v146, v65, s0
	v_mul_f32_e32 v65, 0x3d800000, v152
	v_mul_f32_e32 v72, 0x3fb8aa3b, v155
	v_lshrrev_b32_e32 v15, 16, v58
	v_lshrrev_b32_e32 v59, 16, v14
	v_lshl_add_u64 v[70:71], v[8:9], 0, s[8:9]
	s_lshl_b64 s[8:9], s[60:61], 11
	s_lshl_b64 s[0:1], s[0:1], 11
	v_mul_f32_e32 v68, v65, v68
	v_exp_f32_e32 v72, v72
	ds_write_b16 v173, v58 offset:32768
	ds_write_b16 v160, v178
	ds_write_b16 v160, v14 offset:32768
	ds_write_b16 v179, v180
	ds_write_b16 v179, v15 offset:32768
	ds_write_b16 v181, v182
	ds_write_b16 v181, v59 offset:32768
	v_and_b32_e32 v59, 0xffff0000, v14
	v_lshlrev_b32_e32 v14, 16, v14
	v_lshl_add_u32 v137, s69, 9, v114
	v_lshl_add_u64 v[76:77], v[8:9], 0, s[8:9]
	s_lshl_b64 s[8:9], s[62:63], 11
	v_cvt_pk_bf16_f32 v150, v68, s0
	v_mul_f32_e32 v68, 0x3d800000, v154
	v_mul_f32_e32 v73, 0x3fb8aa3b, v157
	v_or_b32_e32 v59, v59, v15
	v_or_b32_sdwa v58, v14, v58 dst_sel:DWORD dst_unused:UNUSED_PAD src0_sel:DWORD src1_sel:WORD_0
	s_waitcnt vmcnt(15)
	v_lshlrev_b32_e32 v15, 16, v171
	v_lshlrev_b32_e32 v14, 16, v169
	v_mul_f32_e32 v62, 0xbfb8aa3b, v145
	v_lshl_add_u64 v[80:81], v[8:9], 0, s[8:9]
	v_mul_f32_e32 v63, 0xbfb8aa3b, v149
	v_lshl_add_u64 v[78:79], v[8:9], 0, s[0:1]
	s_lshl_b64 s[0:1], s[6:7], 11
	v_mul_f32_e32 v69, v68, v69
	v_exp_f32_e32 v73, v73
	ds_write_b16 v137, v183
	global_store_short v[66:67], v138, off
	global_store_short v[70:71], v141, off
	global_store_short v[76:77], v186, off
	global_store_short v[80:81], v193, off
	s_waitcnt vmcnt(17)
	v_lshlrev_b32_e32 v67, 16, v172
	v_lshlrev_b32_e32 v66, 16, v170
	v_pk_mul_f32 v[14:15], v[56:57], v[14:15]
	v_exp_f32_e32 v62, v62
	v_mul_f32_e32 v64, 0xbfb8aa3b, v147
	v_exp_f32_e32 v63, v63
	v_mul_f32_e32 v65, 0xbfb8aa3b, v151
	v_cvt_pk_bf16_f32 v154, v69, s0
	v_mul_f32_e32 v69, 0x3d800000, v156
	v_mul_f32_e32 v90, 0x3fb8aa3b, v135
	v_cvt_pk_bf16_f32 v56, v14, v15
	v_pk_mul_f32 v[14:15], v[60:61], v[66:67]
	v_exp_f32_e32 v64, v64
	v_exp_f32_e32 v65, v65
	v_lshl_add_u64 v[84:85], v[8:9], 0, s[0:1]
	s_lshl_b64 s[0:1], s[54:55], 11
	v_mul_f32_e32 v69, v69, v72
	v_exp_f32_e32 v136, v90
	v_cvt_pk_bf16_f32 v14, v14, v15
	v_cvt_pk_bf16_f32 v148, v69, s0
	v_mul_f32_e32 v69, 0x3d800000, v158
	v_lshrrev_b32_e32 v15, 16, v14
	v_lshlrev_b32_e32 v159, 16, v159
	v_lshl_add_u32 v139, s10, 9, v115
	v_lshl_add_u32 v142, s11, 9, v116
	v_lshl_add_u32 v140, s13, 9, v118
	v_lshl_add_u64 v[88:89], v[8:9], 0, s[0:1]
	s_lshl_b64 s[0:1], s[48:49], 11
	v_mul_f32_e32 v73, v69, v73
	v_lshrrev_b32_e32 v57, 16, v56
	v_and_b32_e32 v60, 0xffff0000, v14
	v_lshlrev_b32_e32 v66, 16, v14
	ds_write_b16 v137, v56 offset:32768
	ds_write_b16 v139, v138
	ds_write_b16 v139, v14 offset:32768
	ds_write_b16 v142, v141
	ds_write_b16 v142, v57 offset:32768
	ds_write_b16 v192, v186
	ds_write_b16 v192, v15 offset:32768
	ds_write_b16 v140, v193
	s_waitcnt vmcnt(15)
	v_lshlrev_b32_e32 v15, 16, v167
	v_lshlrev_b32_e32 v14, 16, v165
	v_mul_f32_e32 v68, 0xbfb8aa3b, v153
	v_mul_f32_e32 v69, 0xbfb8aa3b, v157
	v_cvt_pk_bf16_f32 v152, v73, s0
	v_mul_f32_e32 v73, 0x3d800000, v159
	v_or_b32_e32 v61, v60, v57
	v_or_b32_sdwa v60, v66, v56 dst_sel:DWORD dst_unused:UNUSED_PAD src0_sel:DWORD src1_sel:WORD_0
	s_waitcnt vmcnt(13)
	v_lshlrev_b32_e32 v57, 16, v168
	v_lshlrev_b32_e32 v56, 16, v166
	v_pk_mul_f32 v[14:15], v[62:63], v[14:15]
	v_exp_f32_e32 v68, v68
	v_mul_f32_e32 v72, 0xbfb8aa3b, v155
	v_exp_f32_e32 v69, v69
	v_mul_f32_e32 v90, v73, v136
	v_mul_f32_e32 v73, 0xbfb8aa3b, v135
	v_cvt_pk_bf16_f32 v62, v14, v15
	v_pk_mul_f32 v[14:15], v[64:65], v[56:57]
	s_lshl_b64 s[8:9], s[56:57], 11
	v_exp_f32_e32 v72, v72
	v_exp_f32_e32 v73, v73
	v_cvt_pk_bf16_f32 v14, v14, v15
	v_lshl_add_u64 v[74:75], v[8:9], 0, s[8:9]
	v_lshl_add_u64 v[82:83], v[8:9], 0, s[0:1]
	s_lshl_b64 s[0:1], s[4:5], 11
	v_lshrrev_b32_e32 v15, 16, v14
	v_lshl_add_u32 v144, s14, 9, v119
	v_lshl_add_u32 v147, s15, 9, v120
	v_lshl_add_u32 v151, s16, 9, v121
	v_lshl_add_u32 v145, s17, 9, v122
	v_lshl_add_u64 v[86:87], v[8:9], 0, s[0:1]
	v_cvt_pk_bf16_f32 v155, v90, s0
	s_lshl_b64 s[0:1], s[42:43], 11
	s_lshl_b32 s66, s3, 10
	global_store_short v[74:75], v143, off
	global_store_short v[78:79], v146, off
	global_store_short v[84:85], v150, off
	global_store_short v[88:89], v154, off
	v_lshrrev_b32_e32 v63, 16, v62
	v_and_b32_e32 v56, 0xffff0000, v14
	v_lshlrev_b32_e32 v64, 16, v14
	ds_write_b16 v140, v62 offset:32768
	ds_write_b16 v144, v143
	ds_write_b16 v144, v14 offset:32768
	ds_write_b16 v147, v146
	ds_write_b16 v147, v63 offset:32768
	ds_write_b16 v151, v150
	ds_write_b16 v151, v15 offset:32768
	ds_write_b16 v145, v154
	s_waitcnt vmcnt(15)
	v_lshlrev_b32_e32 v15, 16, v163
	v_lshlrev_b32_e32 v14, 16, v161
	v_lshl_add_u64 v[90:91], v[8:9], 0, s[0:1]
	v_lshl_add_u64 v[158:159], v[10:11], 0, s[66:67]
	global_store_short v[82:83], v148, off
	global_store_short v[86:87], v152, off
	global_store_short v[90:91], v155, off
	global_store_dwordx4 v[158:159], v[58:61], off
	v_pk_mul_f32 v[14:15], v[68:69], v[14:15]
	v_or_b32_e32 v57, v56, v63
	s_waitcnt vmcnt(17)
	v_lshlrev_b32_e32 v59, 16, v164
	v_lshlrev_b32_e32 v58, 16, v162
	v_cvt_pk_bf16_f32 v60, v14, v15
	v_pk_mul_f32 v[14:15], v[72:73], v[58:59]
	v_or_b32_sdwa v56, v64, v62 dst_sel:DWORD dst_unused:UNUSED_PAD src0_sel:DWORD src1_sel:WORD_0
	v_cvt_pk_bf16_f32 v14, v14, v15
	v_lshrrev_b32_e32 v61, 16, v60
	v_and_b32_e32 v58, 0xffff0000, v14
	v_lshlrev_b32_e32 v62, 16, v14
	v_or_b32_e32 v59, v58, v61
	v_or_b32_sdwa v58, v62, v60 dst_sel:DWORD dst_unused:UNUSED_PAD src0_sel:DWORD src1_sel:WORD_0
	s_add_i32 s3, s3, 1
	v_lshl_add_u32 v149, s18, 9, v123
	v_lshl_add_u32 v153, s19, 9, v124
	v_lshl_add_u32 v156, s20, 9, v125
	v_lshrrev_b32_e32 v15, 16, v14
	ds_write_b16 v145, v60 offset:32768
	ds_write_b16 v149, v148
	ds_write_b16 v149, v14 offset:32768
	ds_write_b16 v153, v152
	ds_write_b16 v153, v61 offset:32768
	ds_write_b16 v156, v155
	ds_write_b16 v156, v15 offset:32768
	global_store_dwordx4 v[158:159], v[56:59], off offset:512
	s_cmp_eq_u32 s3, 4
	s_nop 0
	v_mov_b32_e32 v58, v135
	s_cbranch_scc0 .LBB0_224
	s_ashr_i32 s3, s2, 31
	s_lshl_b64 s[0:1], s[2:3], 10
	v_lshl_add_u64 v[0:1], v[22:23], 0, s[0:1]
	global_store_dword v[0:1], v136, off
	v_mov_b32_e32 v0, 0
	v_mov_b32_e32 v1, 0
	v_mov_b32_e32 v2, 0
	v_mov_b32_e32 v3, 0
	v_mov_b32_e32 v4, 0
	v_mov_b32_e32 v5, 0
	v_mov_b32_e32 v6, 0
	v_mov_b32_e32 v7, 0
	v_mov_b32_e32 v8, 0
	v_mov_b32_e32 v9, 0
	v_mov_b32_e32 v10, 0
	v_mov_b32_e32 v11, 0
	v_mov_b32_e32 v12, 0
	v_mov_b32_e32 v13, 0
	v_mov_b32_e32 v14, 0
	v_mov_b32_e32 v15, 0
	s_waitcnt lgkmcnt(0)
	s_barrier
	s_mov_b64 s[0:1], exec
	v_readlane_b32 s4, v255, 19
	v_readlane_b32 s5, v255, 20
	s_and_b64 s[4:5], s[0:1], s[4:5]
	s_mov_b64 exec, s[4:5]
	s_cbranch_execz .LBB0_222
	v_add_u32_e32 v0, v17, v95
	ds_read_b128 v[0:3], v0
	v_add_u32_e32 v4, v94, v95
	ds_read_b128 v[4:7], v4 offset:32768
	v_add_u32_e32 v56, v17, v96
	ds_read_b128 v[56:59], v56
	v_add_u32_e32 v60, v94, v96
	ds_read_b128 v[60:63], v60 offset:32768
	v_add_u32_e32 v64, v17, v97
	s_waitcnt lgkmcnt(2)
	v_mfma_f32_32x32x16_bf16 v[0:15], v[0:3], v[4:7], 0
	s_waitcnt lgkmcnt(0)
	v_mfma_f32_32x32x16_bf16 v[0:15], v[56:59], v[60:63], v[0:15]
	ds_read_b128 v[56:59], v64
	v_add_u32_e32 v60, v94, v97
	ds_read_b128 v[60:63], v60 offset:32768
	v_add_u32_e32 v64, v17, v98
	s_waitcnt lgkmcnt(0)
	v_mfma_f32_32x32x16_bf16 v[0:15], v[56:59], v[60:63], v[0:15]
	ds_read_b128 v[56:59], v64
	v_add_u32_e32 v60, v94, v98
	ds_read_b128 v[60:63], v60 offset:32768
	v_add_u32_e32 v64, v17, v99
	s_waitcnt lgkmcnt(0)
	v_mfma_f32_32x32x16_bf16 v[0:15], v[56:59], v[60:63], v[0:15]
	ds_read_b128 v[56:59], v64
	v_add_u32_e32 v60, v94, v99
	ds_read_b128 v[60:63], v60 offset:32768
	v_add_u32_e32 v64, v17, v100
	s_waitcnt lgkmcnt(0)
	v_mfma_f32_32x32x16_bf16 v[0:15], v[56:59], v[60:63], v[0:15]
	ds_read_b128 v[56:59], v64
	v_add_u32_e32 v60, v94, v100
	ds_read_b128 v[60:63], v60 offset:32768
	v_add_u32_e32 v64, v17, v101
	s_waitcnt lgkmcnt(0)
	v_mfma_f32_32x32x16_bf16 v[0:15], v[56:59], v[60:63], v[0:15]
	ds_read_b128 v[56:59], v64
	v_add_u32_e32 v60, v94, v101
	ds_read_b128 v[60:63], v60 offset:32768
	v_add_u32_e32 v64, v17, v102
	s_waitcnt lgkmcnt(0)
	v_mfma_f32_32x32x16_bf16 v[0:15], v[56:59], v[60:63], v[0:15]
	ds_read_b128 v[56:59], v64
	v_add_u32_e32 v60, v94, v102
	ds_read_b128 v[60:63], v60 offset:32768
	v_add_u32_e32 v64, v17, v103
	s_waitcnt lgkmcnt(0)
	v_mfma_f32_32x32x16_bf16 v[0:15], v[56:59], v[60:63], v[0:15]
	ds_read_b128 v[56:59], v64
	v_add_u32_e32 v60, v94, v103
	ds_read_b128 v[60:63], v60 offset:32768
	v_add_u32_e32 v64, v17, v104
	s_waitcnt lgkmcnt(0)
	v_mfma_f32_32x32x16_bf16 v[0:15], v[56:59], v[60:63], v[0:15]
	ds_read_b128 v[56:59], v64
	v_add_u32_e32 v60, v94, v104
	ds_read_b128 v[60:63], v60 offset:32768
	v_add_u32_e32 v64, v17, v105
	s_waitcnt lgkmcnt(0)
	v_mfma_f32_32x32x16_bf16 v[0:15], v[56:59], v[60:63], v[0:15]
	ds_read_b128 v[56:59], v64
	v_add_u32_e32 v60, v94, v105
	ds_read_b128 v[60:63], v60 offset:32768
	v_add_u32_e32 v64, v17, v106
	s_waitcnt lgkmcnt(0)
	v_mfma_f32_32x32x16_bf16 v[0:15], v[56:59], v[60:63], v[0:15]
	ds_read_b128 v[56:59], v64
	v_add_u32_e32 v60, v94, v106
	ds_read_b128 v[60:63], v60 offset:32768
	v_add_u32_e32 v64, v17, v107
	s_waitcnt lgkmcnt(0)
	v_mfma_f32_32x32x16_bf16 v[0:15], v[56:59], v[60:63], v[0:15]
	ds_read_b128 v[56:59], v64
	v_add_u32_e32 v60, v94, v107
	ds_read_b128 v[60:63], v60 offset:32768
	v_add_u32_e32 v64, v17, v108
	s_waitcnt lgkmcnt(0)
	v_mfma_f32_32x32x16_bf16 v[0:15], v[56:59], v[60:63], v[0:15]
	ds_read_b128 v[56:59], v64
	v_add_u32_e32 v60, v94, v108
	ds_read_b128 v[60:63], v60 offset:32768
	v_add_u32_e32 v64, v17, v109
	s_waitcnt lgkmcnt(0)
	v_mfma_f32_32x32x16_bf16 v[0:15], v[56:59], v[60:63], v[0:15]
	ds_read_b128 v[56:59], v64
	v_add_u32_e32 v60, v94, v109
	ds_read_b128 v[60:63], v60 offset:32768
	v_add_u32_e32 v64, v17, v110
	s_waitcnt lgkmcnt(0)
	v_mfma_f32_32x32x16_bf16 v[0:15], v[56:59], v[60:63], v[0:15]
	ds_read_b128 v[56:59], v64
	v_add_u32_e32 v60, v94, v110
	ds_read_b128 v[60:63], v60 offset:32768
	s_waitcnt lgkmcnt(0)
	v_mfma_f32_32x32x16_bf16 v[0:15], v[56:59], v[60:63], v[0:15]
	s_branch .LBB0_222
